# v20 + diagonal attention steps pick a mask variant per wave (none / even-wave half / odd-wave half) instead of masking all 64 keys
# baseline (speedup 1.0000x reference)
; __device__ __forceinline__ void cmask(f32x16&p0,f32x16&p1,int jb,int qrel,int hi){
;   const float NEG=-INFINITY; int kb=64*jb+4*hi;
;   #pragma unroll
;   for(int r=0;r<16;++r){int kv=kb+(r&3)+8*(r>>2); if(kv>qrel)p0[r]=NEG; if(kv+32>qrel)p1[r]=NEG;}
; }
.Lat_step_T4:
	s_cmp_eq_u32 s55, 0
	s_cbranch_scc0 .Lat_T4_u
	s_bitcmp1_b32 s46, 5
	s_cbranch_scc1 .Lat_T4_o
	v_add_u32_e32 v243, s16, v204
	ds_read_b64_tr_b16 v[214:215], v243 offset:24576
	ds_read_b64_tr_b16 v[216:217], v243 offset:25088
	v_mfma_f32_32x32x16_bf16 v[80:95], v[176:179], v[144:147], v[64:79]
	v_add_f32_e32 v245, v112, v113
	v_add_f32_e32 v246, v114, v115
	v_add_f32_e32 v245, v116, v245
	v_add_f32_e32 v246, v117, v246
	v_cvt_pk_bf16_f32 v160, v112, v113
	v_cvt_pk_bf16_f32 v161, v114, v115
	ds_read_b64_tr_b16 v[112:113], v243 offset:28672
	ds_read_b64_tr_b16 v[114:115], v243 offset:29184
	v_mfma_f32_32x32x16_bf16 v[96:111], v[180:183], v[144:147], v[64:79]
	v_add_f32_e32 v245, v118, v245
	v_add_f32_e32 v246, v119, v246
	v_add_f32_e32 v245, v120, v245
	v_add_f32_e32 v246, v121, v246
	v_cvt_pk_bf16_f32 v162, v116, v117
	v_cvt_pk_bf16_f32 v163, v118, v119
	ds_read_b64_tr_b16 v[116:117], v243 offset:25600
	ds_read_b64_tr_b16 v[118:119], v243 offset:26112
	v_mfma_f32_32x32x16_bf16 v[80:95], v[184:187], v[148:151], v[80:95]
	v_add_f32_e32 v245, v122, v245
	v_add_f32_e32 v246, v123, v246
	v_add_f32_e32 v245, v124, v245
	v_add_f32_e32 v246, v125, v246
	v_cvt_pk_bf16_f32 v164, v120, v121
	v_cvt_pk_bf16_f32 v165, v122, v123
	ds_read_b64_tr_b16 v[120:121], v243 offset:29696
	ds_read_b64_tr_b16 v[122:123], v243 offset:30208
	v_mfma_f32_32x32x16_bf16 v[96:111], v[188:191], v[148:151], v[96:111]
	v_add_f32_e32 v245, v126, v245
	v_add_f32_e32 v246, v127, v246
	v_add_f32_e32 v245, v128, v245
	v_add_f32_e32 v246, v129, v246
	v_cvt_pk_bf16_f32 v166, v124, v125
	v_cvt_pk_bf16_f32 v167, v126, v127
	ds_read_b64_tr_b16 v[124:125], v243 offset:26624
	ds_read_b64_tr_b16 v[126:127], v243 offset:27136
	v_mfma_f32_32x32x16_bf16 v[80:95], v[192:195], v[152:155], v[80:95]
	v_add_f32_e32 v245, v130, v245
	v_add_f32_e32 v246, v131, v246
	v_add_f32_e32 v245, v132, v245
	v_add_f32_e32 v246, v133, v246
	v_cvt_pk_bf16_f32 v168, v128, v129
	v_cvt_pk_bf16_f32 v169, v130, v131
	ds_read_b64_tr_b16 v[128:129], v243 offset:30720
	ds_read_b64_tr_b16 v[130:131], v243 offset:31232
	v_mfma_f32_32x32x16_bf16 v[96:111], v[196:199], v[152:155], v[96:111]
	v_add_f32_e32 v245, v134, v245
	v_add_f32_e32 v246, v135, v246
	v_add_f32_e32 v245, v136, v245
	v_add_f32_e32 v246, v137, v246
	v_cvt_pk_bf16_f32 v170, v132, v133
	v_cvt_pk_bf16_f32 v171, v134, v135
	ds_read_b64_tr_b16 v[132:133], v243 offset:27648
	ds_read_b64_tr_b16 v[134:135], v243 offset:28160
	v_mfma_f32_32x32x16_bf16 v[80:95], v[200:203], v[156:159], v[80:95]
	v_add_f32_e32 v245, v138, v245
	v_add_f32_e32 v246, v139, v246
	v_add_f32_e32 v245, v140, v245
	v_add_f32_e32 v246, v141, v246
	v_cvt_pk_bf16_f32 v172, v136, v137
	v_cvt_pk_bf16_f32 v173, v138, v139
	ds_read_b64_tr_b16 v[136:137], v243 offset:31744
	ds_read_b64_tr_b16 v[138:139], v243 offset:32256
	v_mfma_f32_32x32x16_bf16 v[96:111], v[206:209], v[156:159], v[96:111]
	v_add_f32_e32 v245, v142, v245
	v_add_f32_e32 v246, v143, v246
	v_add_f32_e32 v245, v245, v246
	v_cvt_pk_bf16_f32 v174, v140, v141
	v_cvt_pk_bf16_f32 v175, v142, v143
	v_add_f32_e32 v211, v211, v245
	v_add_u32_e32 v244, s18, v219
	s_waitcnt lgkmcnt(8)
	v_mfma_f32_32x32x16_bf16 v[0:15], v[160:163], v[214:217], v[0:15]
	v_cmp_gt_i32_e64 s[28:29], 0, v225
	v_cmp_gt_i32_e64 s[30:31], 1, v225
	v_cmp_gt_i32_e64 s[34:35], 2, v225
	v_cndmask_b32_e64 v80, v80, v241, s[28:29]
	v_cmp_gt_i32_e64 s[28:29], 3, v225
	v_cndmask_b32_e64 v81, v81, v241, s[30:31]
	v_cmp_gt_i32_e64 s[30:31], 8, v225
	v_cndmask_b32_e64 v82, v82, v241, s[34:35]
	v_cmp_gt_i32_e64 s[34:35], 9, v225
	v_cndmask_b32_e64 v83, v83, v241, s[28:29]
	ds_read_b64_tr_b16 v[214:215], v243 offset:49152
	ds_read_b64_tr_b16 v[216:217], v243 offset:49664
	v_mfma_f32_32x32x16_bf16 v[16:31], v[160:163], v[112:115], v[16:31]
	s_add_i32 m0, s17, s54
	v_cmp_gt_i32_e64 s[28:29], 10, v225
	v_cndmask_b32_e64 v84, v84, v241, s[30:31]
	v_cmp_gt_i32_e64 s[30:31], 11, v225
	v_cndmask_b32_e64 v85, v85, v241, s[34:35]
	v_cmp_gt_i32_e64 s[34:35], 16, v225
	v_cndmask_b32_e64 v86, v86, v241, s[28:29]
	v_cmp_gt_i32_e64 s[28:29], 17, v225
	v_cndmask_b32_e64 v87, v87, v241, s[30:31]
	v_cmp_gt_i32_e64 s[30:31], 18, v225
	v_cndmask_b32_e64 v88, v88, v241, s[34:35]
	ds_read_b64_tr_b16 v[112:113], v243 offset:53248
	ds_read_b64_tr_b16 v[114:115], v243 offset:53760
	global_load_lds_dwordx4 v222, s[0:1]
	s_add_u32 s0, s0, 0x20000
	s_addc_u32 s1, s1, 0
	v_mfma_f32_32x32x16_bf16 v[0:15], v[164:167], v[116:119], v[0:15]
	s_add_i32 s21, s18, s54
	s_add_i32 m0, s21, 0x6000
	v_cmp_gt_i32_e64 s[34:35], 19, v225
	v_cndmask_b32_e64 v89, v89, v241, s[28:29]
	v_cmp_gt_i32_e64 s[28:29], 24, v225
	v_cndmask_b32_e64 v90, v90, v241, s[30:31]
	v_cmp_gt_i32_e64 s[30:31], 25, v225
	v_cndmask_b32_e64 v91, v91, v241, s[34:35]
	v_cmp_gt_i32_e64 s[34:35], 26, v225
	v_cndmask_b32_e64 v92, v92, v241, s[28:29]
	v_cmp_gt_i32_e64 s[28:29], 27, v225
	v_cndmask_b32_e64 v93, v93, v241, s[30:31]
	ds_read_b64_tr_b16 v[116:117], v243 offset:50176
	ds_read_b64_tr_b16 v[118:119], v243 offset:50688
	global_load_lds_dwordx4 v223, s[4:5]
	v_mfma_f32_32x32x16_bf16 v[16:31], v[164:167], v[120:123], v[16:31]
	s_add_i32 m0, s21, 0xc000
	v_cndmask_b32_e64 v94, v94, v241, s[34:35]
	v_cndmask_b32_e64 v95, v95, v241, s[28:29]
	v_mov_b32_e32 v96, v241
	v_mov_b32_e32 v97, v241
	v_mov_b32_e32 v98, v241
	v_mov_b32_e32 v99, v241
	v_mov_b32_e32 v100, v241
	v_mov_b32_e32 v101, v241
	v_mov_b32_e32 v102, v241
	v_mov_b32_e32 v103, v241
	ds_read_b64_tr_b16 v[120:121], v243 offset:54272
	ds_read_b64_tr_b16 v[122:123], v243 offset:54784
	global_load_lds_dwordx4 v224, s[4:5]
	s_add_u32 s4, s4, 0x20000
	s_addc_u32 s5, s5, 0
	s_waitcnt lgkmcnt(8)
	v_mfma_f32_32x32x16_bf16 v[0:15], v[168:171], v[124:127], v[0:15]
	v_mov_b32_e32 v104, v241
	v_mov_b32_e32 v105, v241
	v_mov_b32_e32 v106, v241
	v_mov_b32_e32 v107, v241
	v_mov_b32_e32 v108, v241
	v_mov_b32_e32 v109, v241
	v_mov_b32_e32 v110, v241
	v_mov_b32_e32 v111, v241
	v_max3_f32 v246, v80, v81, v82
	v_max3_f32 v247, v83, v84, v85
	ds_read_b64_tr_b16 v[124:125], v243 offset:51200
	ds_read_b64_tr_b16 v[126:127], v243 offset:51712
	v_mfma_f32_32x32x16_bf16 v[16:31], v[168:171], v[128:131], v[16:31]
	v_max3_f32 v246, v246, v86, v87
	v_max3_f32 v247, v247, v88, v89
	v_max3_f32 v246, v246, v90, v91
	v_max3_f32 v247, v247, v92, v93
	v_max3_f32 v246, v246, v94, v95
	v_max3_f32 v247, v247, v96, v97
	v_max3_f32 v246, v246, v98, v99
	v_max3_f32 v247, v247, v100, v101
	v_max3_f32 v246, v246, v102, v103
	v_max3_f32 v247, v247, v104, v105
	ds_read_b64_tr_b16 v[128:129], v243 offset:55296
	ds_read_b64_tr_b16 v[130:131], v243 offset:55808
	v_mfma_f32_32x32x16_bf16 v[0:15], v[172:175], v[132:135], v[0:15]
	v_max3_f32 v246, v246, v106, v107
	v_max3_f32 v247, v247, v108, v109
	v_max3_f32 v246, v246, v110, v111
	v_max_f32_e32 v248, v246, v247
	ds_read_b64_tr_b16 v[132:133], v243 offset:52224
	ds_read_b64_tr_b16 v[134:135], v243 offset:52736
	v_mfma_f32_32x32x16_bf16 v[16:31], v[172:175], v[136:139], v[16:31]
	ds_read_b64_tr_b16 v[136:137], v243 offset:56320
	ds_read_b64_tr_b16 v[138:139], v243 offset:56832
	s_waitcnt lgkmcnt(8)
	v_mfma_f32_32x32x16_bf16 v[32:47], v[160:163], v[214:217], v[32:47]
	ds_read_b128 v[176:179], v244 offset:0
	ds_read_b128 v[180:183], v244 offset:512
	v_cmp_lt_f32_e32 vcc, s87, v248
	s_cbranch_vccnz .Lat_rare_T4e
.Lat_cont_T4e:
	v_mfma_f32_32x32x16_bf16 v[48:63], v[160:163], v[112:115], v[48:63]
	v_exp_f32_e32 v80, v80
	v_exp_f32_e32 v81, v81
	v_exp_f32_e32 v82, v82
	v_exp_f32_e32 v83, v83
	v_exp_f32_e32 v84, v84
	ds_read_b128 v[184:187], v244 offset:2048
	ds_read_b128 v[188:191], v244 offset:2560
	v_mfma_f32_32x32x16_bf16 v[32:47], v[164:167], v[116:119], v[32:47]
	v_exp_f32_e32 v85, v85
	v_exp_f32_e32 v86, v86
	v_exp_f32_e32 v87, v87
	v_exp_f32_e32 v88, v88
	v_exp_f32_e32 v89, v89
	ds_read_b128 v[192:195], v244 offset:4096
	ds_read_b128 v[196:199], v244 offset:4608
	v_mfma_f32_32x32x16_bf16 v[48:63], v[164:167], v[120:123], v[48:63]
	v_exp_f32_e32 v90, v90
	v_exp_f32_e32 v91, v91
	v_exp_f32_e32 v92, v92
	v_exp_f32_e32 v93, v93
	v_exp_f32_e32 v94, v94
	ds_read_b128 v[200:203], v244 offset:6144
	ds_read_b128 v[206:209], v244 offset:6656
	s_waitcnt lgkmcnt(8)
	v_mfma_f32_32x32x16_bf16 v[32:47], v[168:171], v[124:127], v[32:47]
	v_exp_f32_e32 v95, v95
	v_exp_f32_e32 v96, v96
	v_exp_f32_e32 v97, v97
	v_exp_f32_e32 v98, v98
	v_exp_f32_e32 v99, v99
	v_mfma_f32_32x32x16_bf16 v[48:63], v[168:171], v[128:131], v[48:63]
	v_exp_f32_e32 v100, v100
	v_exp_f32_e32 v101, v101
	v_exp_f32_e32 v102, v102
	v_exp_f32_e32 v103, v103
	v_mfma_f32_32x32x16_bf16 v[32:47], v[172:175], v[132:135], v[32:47]
	v_exp_f32_e32 v104, v104
	v_exp_f32_e32 v105, v105
	v_exp_f32_e32 v106, v106
	v_exp_f32_e32 v107, v107
	v_mfma_f32_32x32x16_bf16 v[48:63], v[172:175], v[136:139], v[48:63]
	v_exp_f32_e32 v108, v108
	v_exp_f32_e32 v109, v109
	v_exp_f32_e32 v110, v110
	v_exp_f32_e32 v111, v111
	s_waitcnt vmcnt(3) lgkmcnt(0)
	s_barrier
	s_cbranch_vccnz .Lat_resc_T4e
.Lat_noresc_T4e:
	s_mov_b32 s21, s16
	s_mov_b32 s16, s17
	s_mov_b32 s17, s18
	s_mov_b32 s18, s21
	s_branch .Lat_T4_end
.Lat_T4_o:
	v_add_u32_e32 v243, s16, v204
	ds_read_b64_tr_b16 v[214:215], v243 offset:24576
	ds_read_b64_tr_b16 v[216:217], v243 offset:25088
	v_mfma_f32_32x32x16_bf16 v[80:95], v[176:179], v[144:147], v[64:79]
	v_add_f32_e32 v245, v112, v113
	v_add_f32_e32 v246, v114, v115
	v_add_f32_e32 v245, v116, v245
	v_add_f32_e32 v246, v117, v246
	v_cvt_pk_bf16_f32 v160, v112, v113
	v_cvt_pk_bf16_f32 v161, v114, v115
	ds_read_b64_tr_b16 v[112:113], v243 offset:28672
	ds_read_b64_tr_b16 v[114:115], v243 offset:29184
	v_mfma_f32_32x32x16_bf16 v[96:111], v[180:183], v[144:147], v[64:79]
	v_add_f32_e32 v245, v118, v245
	v_add_f32_e32 v246, v119, v246
	v_add_f32_e32 v245, v120, v245
	v_add_f32_e32 v246, v121, v246
	v_cvt_pk_bf16_f32 v162, v116, v117
	v_cvt_pk_bf16_f32 v163, v118, v119
	ds_read_b64_tr_b16 v[116:117], v243 offset:25600
	ds_read_b64_tr_b16 v[118:119], v243 offset:26112
	v_mfma_f32_32x32x16_bf16 v[80:95], v[184:187], v[148:151], v[80:95]
	v_add_f32_e32 v245, v122, v245
	v_add_f32_e32 v246, v123, v246
	v_add_f32_e32 v245, v124, v245
	v_add_f32_e32 v246, v125, v246
	v_cvt_pk_bf16_f32 v164, v120, v121
	v_cvt_pk_bf16_f32 v165, v122, v123
	ds_read_b64_tr_b16 v[120:121], v243 offset:29696
	ds_read_b64_tr_b16 v[122:123], v243 offset:30208
	v_mfma_f32_32x32x16_bf16 v[96:111], v[188:191], v[148:151], v[96:111]
	v_add_f32_e32 v245, v126, v245
	v_add_f32_e32 v246, v127, v246
	v_add_f32_e32 v245, v128, v245
	v_add_f32_e32 v246, v129, v246
	v_cvt_pk_bf16_f32 v166, v124, v125
	v_cvt_pk_bf16_f32 v167, v126, v127
	ds_read_b64_tr_b16 v[124:125], v243 offset:26624
	ds_read_b64_tr_b16 v[126:127], v243 offset:27136
	v_mfma_f32_32x32x16_bf16 v[80:95], v[192:195], v[152:155], v[80:95]
	v_add_f32_e32 v245, v130, v245
	v_add_f32_e32 v246, v131, v246
	v_add_f32_e32 v245, v132, v245
	v_add_f32_e32 v246, v133, v246
	v_cvt_pk_bf16_f32 v168, v128, v129
	v_cvt_pk_bf16_f32 v169, v130, v131
	ds_read_b64_tr_b16 v[128:129], v243 offset:30720
	ds_read_b64_tr_b16 v[130:131], v243 offset:31232
	v_mfma_f32_32x32x16_bf16 v[96:111], v[196:199], v[152:155], v[96:111]
	v_add_f32_e32 v245, v134, v245
	v_add_f32_e32 v246, v135, v246
	v_add_f32_e32 v245, v136, v245
	v_add_f32_e32 v246, v137, v246
	v_cvt_pk_bf16_f32 v170, v132, v133
	v_cvt_pk_bf16_f32 v171, v134, v135
	ds_read_b64_tr_b16 v[132:133], v243 offset:27648
	ds_read_b64_tr_b16 v[134:135], v243 offset:28160
	v_mfma_f32_32x32x16_bf16 v[80:95], v[200:203], v[156:159], v[80:95]
	v_add_f32_e32 v245, v138, v245
	v_add_f32_e32 v246, v139, v246
	v_add_f32_e32 v245, v140, v245
	v_add_f32_e32 v246, v141, v246
	v_cvt_pk_bf16_f32 v172, v136, v137
	v_cvt_pk_bf16_f32 v173, v138, v139
	ds_read_b64_tr_b16 v[136:137], v243 offset:31744
	ds_read_b64_tr_b16 v[138:139], v243 offset:32256
	v_mfma_f32_32x32x16_bf16 v[96:111], v[206:209], v[156:159], v[96:111]
	v_add_f32_e32 v245, v142, v245
	v_add_f32_e32 v246, v143, v246
	v_add_f32_e32 v245, v245, v246
	v_cvt_pk_bf16_f32 v174, v140, v141
	v_cvt_pk_bf16_f32 v175, v142, v143
	v_add_f32_e32 v211, v211, v245
	v_add_u32_e32 v244, s18, v219
	s_waitcnt lgkmcnt(8)
	v_mfma_f32_32x32x16_bf16 v[0:15], v[160:163], v[214:217], v[0:15]
	v_cmp_gt_i32_e64 s[28:29], 32, v225
	v_cmp_gt_i32_e64 s[30:31], 33, v225
	v_cmp_gt_i32_e64 s[34:35], 34, v225
	v_cndmask_b32_e64 v96, v96, v241, s[28:29]
	v_cmp_gt_i32_e64 s[28:29], 35, v225
	v_cndmask_b32_e64 v97, v97, v241, s[30:31]
	v_cmp_gt_i32_e64 s[30:31], 40, v225
	v_cndmask_b32_e64 v98, v98, v241, s[34:35]
	v_cmp_gt_i32_e64 s[34:35], 41, v225
	v_cndmask_b32_e64 v99, v99, v241, s[28:29]
	ds_read_b64_tr_b16 v[214:215], v243 offset:49152
	ds_read_b64_tr_b16 v[216:217], v243 offset:49664
	v_mfma_f32_32x32x16_bf16 v[16:31], v[160:163], v[112:115], v[16:31]
	s_add_i32 m0, s17, s54
	v_cmp_gt_i32_e64 s[28:29], 42, v225
	v_cndmask_b32_e64 v100, v100, v241, s[30:31]
	v_cmp_gt_i32_e64 s[30:31], 43, v225
	v_cndmask_b32_e64 v101, v101, v241, s[34:35]
	v_cmp_gt_i32_e64 s[34:35], 48, v225
	v_cndmask_b32_e64 v102, v102, v241, s[28:29]
	v_cmp_gt_i32_e64 s[28:29], 49, v225
	v_cndmask_b32_e64 v103, v103, v241, s[30:31]
	v_cmp_gt_i32_e64 s[30:31], 50, v225
	v_cndmask_b32_e64 v104, v104, v241, s[34:35]
	ds_read_b64_tr_b16 v[112:113], v243 offset:53248
	ds_read_b64_tr_b16 v[114:115], v243 offset:53760
	global_load_lds_dwordx4 v222, s[0:1]
	s_add_u32 s0, s0, 0x20000
	s_addc_u32 s1, s1, 0
	v_mfma_f32_32x32x16_bf16 v[0:15], v[164:167], v[116:119], v[0:15]
	s_add_i32 s21, s18, s54
	s_add_i32 m0, s21, 0x6000
	v_cmp_gt_i32_e64 s[34:35], 51, v225
	v_cndmask_b32_e64 v105, v105, v241, s[28:29]
	v_cmp_gt_i32_e64 s[28:29], 56, v225
	v_cndmask_b32_e64 v106, v106, v241, s[30:31]
	v_cmp_gt_i32_e64 s[30:31], 57, v225
	v_cndmask_b32_e64 v107, v107, v241, s[34:35]
	v_cmp_gt_i32_e64 s[34:35], 58, v225
	v_cndmask_b32_e64 v108, v108, v241, s[28:29]
	v_cmp_gt_i32_e64 s[28:29], 59, v225
	v_cndmask_b32_e64 v109, v109, v241, s[30:31]
	ds_read_b64_tr_b16 v[116:117], v243 offset:50176
	ds_read_b64_tr_b16 v[118:119], v243 offset:50688
	global_load_lds_dwordx4 v223, s[4:5]
	v_mfma_f32_32x32x16_bf16 v[16:31], v[164:167], v[120:123], v[16:31]
	s_add_i32 m0, s21, 0xc000
	v_cndmask_b32_e64 v110, v110, v241, s[34:35]
	v_cndmask_b32_e64 v111, v111, v241, s[28:29]
	v_max3_f32 v246, v80, v81, v82
	v_max3_f32 v247, v83, v84, v85
	v_max3_f32 v246, v246, v86, v87
	v_max3_f32 v247, v247, v88, v89
	v_max3_f32 v246, v246, v90, v91
	v_max3_f32 v247, v247, v92, v93
	v_max3_f32 v246, v246, v94, v95
	v_max3_f32 v247, v247, v96, v97
	ds_read_b64_tr_b16 v[120:121], v243 offset:54272
	ds_read_b64_tr_b16 v[122:123], v243 offset:54784
	global_load_lds_dwordx4 v224, s[4:5]
	s_add_u32 s4, s4, 0x20000
	s_addc_u32 s5, s5, 0
	s_waitcnt lgkmcnt(8)
	v_mfma_f32_32x32x16_bf16 v[0:15], v[168:171], v[124:127], v[0:15]
	v_max3_f32 v246, v246, v98, v99
	v_max3_f32 v247, v247, v100, v101
	v_max3_f32 v246, v246, v102, v103
	v_max3_f32 v247, v247, v104, v105
	v_max3_f32 v246, v246, v106, v107
	v_max3_f32 v247, v247, v108, v109
	v_max3_f32 v246, v246, v110, v111
	v_max_f32_e32 v248, v246, v247
	ds_read_b64_tr_b16 v[124:125], v243 offset:51200
	ds_read_b64_tr_b16 v[126:127], v243 offset:51712
	v_mfma_f32_32x32x16_bf16 v[16:31], v[168:171], v[128:131], v[16:31]
	ds_read_b64_tr_b16 v[128:129], v243 offset:55296
	ds_read_b64_tr_b16 v[130:131], v243 offset:55808
	v_mfma_f32_32x32x16_bf16 v[0:15], v[172:175], v[132:135], v[0:15]
	ds_read_b64_tr_b16 v[132:133], v243 offset:52224
	ds_read_b64_tr_b16 v[134:135], v243 offset:52736
	v_mfma_f32_32x32x16_bf16 v[16:31], v[172:175], v[136:139], v[16:31]
	ds_read_b64_tr_b16 v[136:137], v243 offset:56320
	ds_read_b64_tr_b16 v[138:139], v243 offset:56832
	s_waitcnt lgkmcnt(8)
	v_mfma_f32_32x32x16_bf16 v[32:47], v[160:163], v[214:217], v[32:47]
	ds_read_b128 v[176:179], v244 offset:0
	ds_read_b128 v[180:183], v244 offset:512
	v_cmp_lt_f32_e32 vcc, s87, v248
	s_cbranch_vccnz .Lat_rare_T4o
.Lat_cont_T4o:
	v_mfma_f32_32x32x16_bf16 v[48:63], v[160:163], v[112:115], v[48:63]
	v_exp_f32_e32 v80, v80
	v_exp_f32_e32 v81, v81
	v_exp_f32_e32 v82, v82
	v_exp_f32_e32 v83, v83
	v_exp_f32_e32 v84, v84
	ds_read_b128 v[184:187], v244 offset:2048
	ds_read_b128 v[188:191], v244 offset:2560
	v_mfma_f32_32x32x16_bf16 v[32:47], v[164:167], v[116:119], v[32:47]
	v_exp_f32_e32 v85, v85
	v_exp_f32_e32 v86, v86
	v_exp_f32_e32 v87, v87
	v_exp_f32_e32 v88, v88
	v_exp_f32_e32 v89, v89
	ds_read_b128 v[192:195], v244 offset:4096
	ds_read_b128 v[196:199], v244 offset:4608
	v_mfma_f32_32x32x16_bf16 v[48:63], v[164:167], v[120:123], v[48:63]
	v_exp_f32_e32 v90, v90
	v_exp_f32_e32 v91, v91
	v_exp_f32_e32 v92, v92
	v_exp_f32_e32 v93, v93
	v_exp_f32_e32 v94, v94
	ds_read_b128 v[200:203], v244 offset:6144
	ds_read_b128 v[206:209], v244 offset:6656
	s_waitcnt lgkmcnt(8)
	v_mfma_f32_32x32x16_bf16 v[32:47], v[168:171], v[124:127], v[32:47]
	v_exp_f32_e32 v95, v95
	v_exp_f32_e32 v96, v96
	v_exp_f32_e32 v97, v97
	v_exp_f32_e32 v98, v98
	v_exp_f32_e32 v99, v99
	v_mfma_f32_32x32x16_bf16 v[48:63], v[168:171], v[128:131], v[48:63]
	v_exp_f32_e32 v100, v100
	v_exp_f32_e32 v101, v101
	v_exp_f32_e32 v102, v102
	v_exp_f32_e32 v103, v103
	v_mfma_f32_32x32x16_bf16 v[32:47], v[172:175], v[132:135], v[32:47]
	v_exp_f32_e32 v104, v104
	v_exp_f32_e32 v105, v105
	v_exp_f32_e32 v106, v106
	v_exp_f32_e32 v107, v107
	v_mfma_f32_32x32x16_bf16 v[48:63], v[172:175], v[136:139], v[48:63]
	v_exp_f32_e32 v108, v108
	v_exp_f32_e32 v109, v109
	v_exp_f32_e32 v110, v110
	v_exp_f32_e32 v111, v111
	s_waitcnt vmcnt(3) lgkmcnt(0)
	s_barrier
	s_cbranch_vccnz .Lat_resc_T4o
.Lat_noresc_T4o:
	s_mov_b32 s21, s16
	s_mov_b32 s16, s17
	s_mov_b32 s17, s18
	s_mov_b32 s18, s21
	s_branch .Lat_T4_end
.Lat_T4_u:
	v_add_u32_e32 v243, s16, v204
	ds_read_b64_tr_b16 v[214:215], v243 offset:24576
	ds_read_b64_tr_b16 v[216:217], v243 offset:25088
	v_mfma_f32_32x32x16_bf16 v[80:95], v[176:179], v[144:147], v[64:79]
	v_add_f32_e32 v245, v112, v113
	v_add_f32_e32 v246, v114, v115
	v_add_f32_e32 v245, v116, v245
	v_add_f32_e32 v246, v117, v246
	v_cvt_pk_bf16_f32 v160, v112, v113
	v_cvt_pk_bf16_f32 v161, v114, v115
	ds_read_b64_tr_b16 v[112:113], v243 offset:28672
	ds_read_b64_tr_b16 v[114:115], v243 offset:29184
	v_mfma_f32_32x32x16_bf16 v[96:111], v[180:183], v[144:147], v[64:79]
	v_add_f32_e32 v245, v118, v245
	v_add_f32_e32 v246, v119, v246
	v_add_f32_e32 v245, v120, v245
	v_add_f32_e32 v246, v121, v246
	v_cvt_pk_bf16_f32 v162, v116, v117
	v_cvt_pk_bf16_f32 v163, v118, v119
	ds_read_b64_tr_b16 v[116:117], v243 offset:25600
	ds_read_b64_tr_b16 v[118:119], v243 offset:26112
	v_mfma_f32_32x32x16_bf16 v[80:95], v[184:187], v[148:151], v[80:95]
	v_add_f32_e32 v245, v122, v245
	v_add_f32_e32 v246, v123, v246
	v_add_f32_e32 v245, v124, v245
	v_add_f32_e32 v246, v125, v246
	v_cvt_pk_bf16_f32 v164, v120, v121
	v_cvt_pk_bf16_f32 v165, v122, v123
	ds_read_b64_tr_b16 v[120:121], v243 offset:29696
	ds_read_b64_tr_b16 v[122:123], v243 offset:30208
	v_mfma_f32_32x32x16_bf16 v[96:111], v[188:191], v[148:151], v[96:111]
	v_add_f32_e32 v245, v126, v245
	v_add_f32_e32 v246, v127, v246
	v_add_f32_e32 v245, v128, v245
	v_add_f32_e32 v246, v129, v246
	v_cvt_pk_bf16_f32 v166, v124, v125
	v_cvt_pk_bf16_f32 v167, v126, v127
	ds_read_b64_tr_b16 v[124:125], v243 offset:26624
	ds_read_b64_tr_b16 v[126:127], v243 offset:27136
	v_mfma_f32_32x32x16_bf16 v[80:95], v[192:195], v[152:155], v[80:95]
	v_add_f32_e32 v245, v130, v245
	v_add_f32_e32 v246, v131, v246
	v_add_f32_e32 v245, v132, v245
	v_add_f32_e32 v246, v133, v246
	v_cvt_pk_bf16_f32 v168, v128, v129
	v_cvt_pk_bf16_f32 v169, v130, v131
	ds_read_b64_tr_b16 v[128:129], v243 offset:30720
	ds_read_b64_tr_b16 v[130:131], v243 offset:31232
	v_mfma_f32_32x32x16_bf16 v[96:111], v[196:199], v[152:155], v[96:111]
	v_add_f32_e32 v245, v134, v245
	v_add_f32_e32 v246, v135, v246
	v_add_f32_e32 v245, v136, v245
	v_add_f32_e32 v246, v137, v246
	v_cvt_pk_bf16_f32 v170, v132, v133
	v_cvt_pk_bf16_f32 v171, v134, v135
	ds_read_b64_tr_b16 v[132:133], v243 offset:27648
	ds_read_b64_tr_b16 v[134:135], v243 offset:28160
	v_mfma_f32_32x32x16_bf16 v[80:95], v[200:203], v[156:159], v[80:95]
	v_add_f32_e32 v245, v138, v245
	v_add_f32_e32 v246, v139, v246
	v_add_f32_e32 v245, v140, v245
	v_add_f32_e32 v246, v141, v246
	v_cvt_pk_bf16_f32 v172, v136, v137
	v_cvt_pk_bf16_f32 v173, v138, v139
	ds_read_b64_tr_b16 v[136:137], v243 offset:31744
	ds_read_b64_tr_b16 v[138:139], v243 offset:32256
	v_mfma_f32_32x32x16_bf16 v[96:111], v[206:209], v[156:159], v[96:111]
	v_add_f32_e32 v245, v142, v245
	v_add_f32_e32 v246, v143, v246
	v_add_f32_e32 v245, v245, v246
	v_cvt_pk_bf16_f32 v174, v140, v141
	v_cvt_pk_bf16_f32 v175, v142, v143
	v_add_f32_e32 v211, v211, v245
	v_add_u32_e32 v244, s18, v219
	s_waitcnt lgkmcnt(8)
	v_mfma_f32_32x32x16_bf16 v[0:15], v[160:163], v[214:217], v[0:15]
	v_max3_f32 v246, v80, v81, v82
	v_max3_f32 v247, v83, v84, v85
	ds_read_b64_tr_b16 v[214:215], v243 offset:49152
	ds_read_b64_tr_b16 v[216:217], v243 offset:49664
	v_mfma_f32_32x32x16_bf16 v[16:31], v[160:163], v[112:115], v[16:31]
	s_add_i32 m0, s17, s54
	v_max3_f32 v246, v246, v86, v87
	v_max3_f32 v247, v247, v88, v89
	v_max3_f32 v246, v246, v90, v91
	v_max3_f32 v247, v247, v92, v93
	ds_read_b64_tr_b16 v[112:113], v243 offset:53248
	ds_read_b64_tr_b16 v[114:115], v243 offset:53760
	global_load_lds_dwordx4 v222, s[0:1]
	s_add_u32 s0, s0, 0x20000
	s_addc_u32 s1, s1, 0
	v_mfma_f32_32x32x16_bf16 v[0:15], v[164:167], v[116:119], v[0:15]
	s_add_i32 s21, s18, s54
	s_add_i32 m0, s21, 0x6000
	v_max3_f32 v246, v246, v94, v95
	v_max3_f32 v247, v247, v96, v97
	v_max3_f32 v246, v246, v98, v99
	v_max3_f32 v247, v247, v100, v101
	ds_read_b64_tr_b16 v[116:117], v243 offset:50176
	ds_read_b64_tr_b16 v[118:119], v243 offset:50688
	global_load_lds_dwordx4 v223, s[4:5]
	v_mfma_f32_32x32x16_bf16 v[16:31], v[164:167], v[120:123], v[16:31]
	s_add_i32 m0, s21, 0xc000
	v_max3_f32 v246, v246, v102, v103
	v_max3_f32 v247, v247, v104, v105
	v_max3_f32 v246, v246, v106, v107
	v_max3_f32 v247, v247, v108, v109
	ds_read_b64_tr_b16 v[120:121], v243 offset:54272
	ds_read_b64_tr_b16 v[122:123], v243 offset:54784
	global_load_lds_dwordx4 v224, s[4:5]
	s_add_u32 s4, s4, 0x20000
	s_addc_u32 s5, s5, 0
	s_waitcnt lgkmcnt(8)
	v_mfma_f32_32x32x16_bf16 v[0:15], v[168:171], v[124:127], v[0:15]
	v_max3_f32 v246, v246, v110, v111
	v_max_f32_e32 v248, v246, v247
	ds_read_b64_tr_b16 v[124:125], v243 offset:51200
	ds_read_b64_tr_b16 v[126:127], v243 offset:51712
	v_cmp_lt_f32_e32 vcc, s87, v248
	s_cbranch_vccnz .Lat_rare_T4u

.Lat_T4_end:
.Lat_step_T3:
	s_cmp_lt_u32 s55, 1
	s_cbranch_scc1 .Lat_T3_light
	s_cmp_eq_u32 s55, 1
	s_cbranch_scc0 .Lat_T3_u
	s_bitcmp1_b32 s46, 5
	s_cbranch_scc1 .Lat_T3_o
	v_add_u32_e32 v243, s16, v204
	ds_read_b64_tr_b16 v[214:215], v243 offset:24576
	ds_read_b64_tr_b16 v[216:217], v243 offset:25088
	v_mfma_f32_32x32x16_bf16 v[112:127], v[176:179], v[144:147], v[64:79]
	v_add_f32_e32 v245, v80, v81
	v_add_f32_e32 v246, v82, v83
	v_add_f32_e32 v245, v84, v245
	v_add_f32_e32 v246, v85, v246
	v_cvt_pk_bf16_f32 v160, v80, v81
	v_cvt_pk_bf16_f32 v161, v82, v83
	ds_read_b64_tr_b16 v[80:81], v243 offset:28672
	ds_read_b64_tr_b16 v[82:83], v243 offset:29184
	v_mfma_f32_32x32x16_bf16 v[128:143], v[180:183], v[144:147], v[64:79]
	v_add_f32_e32 v245, v86, v245
	v_add_f32_e32 v246, v87, v246
	v_add_f32_e32 v245, v88, v245
	v_add_f32_e32 v246, v89, v246
	v_cvt_pk_bf16_f32 v162, v84, v85
	v_cvt_pk_bf16_f32 v163, v86, v87
	ds_read_b64_tr_b16 v[84:85], v243 offset:25600
	ds_read_b64_tr_b16 v[86:87], v243 offset:26112
	v_mfma_f32_32x32x16_bf16 v[112:127], v[184:187], v[148:151], v[112:127]
	v_add_f32_e32 v245, v90, v245
	v_add_f32_e32 v246, v91, v246
	v_add_f32_e32 v245, v92, v245
	v_add_f32_e32 v246, v93, v246
	v_cvt_pk_bf16_f32 v164, v88, v89
	v_cvt_pk_bf16_f32 v165, v90, v91
	ds_read_b64_tr_b16 v[88:89], v243 offset:29696
	ds_read_b64_tr_b16 v[90:91], v243 offset:30208
	v_mfma_f32_32x32x16_bf16 v[128:143], v[188:191], v[148:151], v[128:143]
	v_add_f32_e32 v245, v94, v245
	v_add_f32_e32 v246, v95, v246
	v_add_f32_e32 v245, v96, v245
	v_add_f32_e32 v246, v97, v246
	v_cvt_pk_bf16_f32 v166, v92, v93
	v_cvt_pk_bf16_f32 v167, v94, v95
	ds_read_b64_tr_b16 v[92:93], v243 offset:26624
	ds_read_b64_tr_b16 v[94:95], v243 offset:27136
	v_mfma_f32_32x32x16_bf16 v[112:127], v[192:195], v[152:155], v[112:127]
	v_add_f32_e32 v245, v98, v245
	v_add_f32_e32 v246, v99, v246
	v_add_f32_e32 v245, v100, v245
	v_add_f32_e32 v246, v101, v246
	v_cvt_pk_bf16_f32 v168, v96, v97
	v_cvt_pk_bf16_f32 v169, v98, v99
	ds_read_b64_tr_b16 v[96:97], v243 offset:30720
	ds_read_b64_tr_b16 v[98:99], v243 offset:31232
	v_mfma_f32_32x32x16_bf16 v[128:143], v[196:199], v[152:155], v[128:143]
	v_add_f32_e32 v245, v102, v245
	v_add_f32_e32 v246, v103, v246
	v_add_f32_e32 v245, v104, v245
	v_add_f32_e32 v246, v105, v246
	v_cvt_pk_bf16_f32 v170, v100, v101
	v_cvt_pk_bf16_f32 v171, v102, v103
	ds_read_b64_tr_b16 v[100:101], v243 offset:27648
	ds_read_b64_tr_b16 v[102:103], v243 offset:28160
	v_mfma_f32_32x32x16_bf16 v[112:127], v[200:203], v[156:159], v[112:127]
	v_add_f32_e32 v245, v106, v245
	v_add_f32_e32 v246, v107, v246
	v_add_f32_e32 v245, v108, v245
	v_add_f32_e32 v246, v109, v246
	v_cvt_pk_bf16_f32 v172, v104, v105
	v_cvt_pk_bf16_f32 v173, v106, v107
	ds_read_b64_tr_b16 v[104:105], v243 offset:31744
	ds_read_b64_tr_b16 v[106:107], v243 offset:32256
	v_mfma_f32_32x32x16_bf16 v[128:143], v[206:209], v[156:159], v[128:143]
	v_add_f32_e32 v245, v110, v245
	v_add_f32_e32 v246, v111, v246
	v_add_f32_e32 v245, v245, v246
	v_cvt_pk_bf16_f32 v174, v108, v109
	v_cvt_pk_bf16_f32 v175, v110, v111
	v_add_f32_e32 v211, v211, v245
	v_add_u32_e32 v244, s18, v219
	s_waitcnt lgkmcnt(8)
; __device__ __forceinline__ void cmask(f32x16&p0,f32x16&p1,int jb,int qrel,int hi){
;   const float NEG=-INFINITY; int kb=64*jb+4*hi;
;   #pragma unroll
;   for(int r=0;r<16;++r){int kv=kb+(r&3)+8*(r>>2); if(kv>qrel)p0[r]=NEG; if(kv+32>qrel)p1[r]=NEG;}
; }
	v_mfma_f32_32x32x16_bf16 v[0:15], v[160:163], v[214:217], v[0:15]
	v_add_u32_e32 v242, 0xffffffc0, v225
	v_cmp_gt_i32_e64 s[28:29], 0, v242
	v_cmp_gt_i32_e64 s[30:31], 1, v242
	v_cmp_gt_i32_e64 s[34:35], 2, v242
	v_cndmask_b32_e64 v112, v112, v241, s[28:29]
	v_cmp_gt_i32_e64 s[28:29], 3, v242
	v_cndmask_b32_e64 v113, v113, v241, s[30:31]
	v_cmp_gt_i32_e64 s[30:31], 8, v242
	v_cndmask_b32_e64 v114, v114, v241, s[34:35]
	v_cmp_gt_i32_e64 s[34:35], 9, v242
	ds_read_b64_tr_b16 v[214:215], v243 offset:49152
	ds_read_b64_tr_b16 v[216:217], v243 offset:49664
	v_mfma_f32_32x32x16_bf16 v[16:31], v[160:163], v[80:83], v[16:31]
	v_cndmask_b32_e64 v115, v115, v241, s[28:29]
	v_cmp_gt_i32_e64 s[28:29], 10, v242
	v_cndmask_b32_e64 v116, v116, v241, s[30:31]
	v_cmp_gt_i32_e64 s[30:31], 11, v242
	v_cndmask_b32_e64 v117, v117, v241, s[34:35]
	v_cmp_gt_i32_e64 s[34:35], 16, v242
	v_cndmask_b32_e64 v118, v118, v241, s[28:29]
	v_cmp_gt_i32_e64 s[28:29], 17, v242
	v_cndmask_b32_e64 v119, v119, v241, s[30:31]
	v_cmp_gt_i32_e64 s[30:31], 18, v242
	ds_read_b64_tr_b16 v[80:81], v243 offset:53248
	ds_read_b64_tr_b16 v[82:83], v243 offset:53760
	v_mfma_f32_32x32x16_bf16 v[0:15], v[164:167], v[84:87], v[0:15]
	s_add_i32 s21, s18, s54
	s_add_i32 m0, s21, 0x6000
	v_cndmask_b32_e64 v120, v120, v241, s[34:35]
	v_cmp_gt_i32_e64 s[34:35], 19, v242
	v_cndmask_b32_e64 v121, v121, v241, s[28:29]
	v_cmp_gt_i32_e64 s[28:29], 24, v242
	v_cndmask_b32_e64 v122, v122, v241, s[30:31]
	v_cmp_gt_i32_e64 s[30:31], 25, v242
	v_cndmask_b32_e64 v123, v123, v241, s[34:35]
	v_cmp_gt_i32_e64 s[34:35], 26, v242
	v_cndmask_b32_e64 v124, v124, v241, s[28:29]
	v_cmp_gt_i32_e64 s[28:29], 27, v242
	ds_read_b64_tr_b16 v[84:85], v243 offset:50176
	ds_read_b64_tr_b16 v[86:87], v243 offset:50688
	global_load_lds_dwordx4 v223, s[4:5]
	v_mfma_f32_32x32x16_bf16 v[16:31], v[164:167], v[88:91], v[16:31]
	s_add_i32 m0, s21, 0xc000
	v_cndmask_b32_e64 v125, v125, v241, s[30:31]
	v_cndmask_b32_e64 v126, v126, v241, s[34:35]
	v_cndmask_b32_e64 v127, v127, v241, s[28:29]
	v_mov_b32_e32 v128, v241
	v_mov_b32_e32 v129, v241
	v_mov_b32_e32 v130, v241
	v_mov_b32_e32 v131, v241
	v_mov_b32_e32 v132, v241
	v_mov_b32_e32 v133, v241
	v_mov_b32_e32 v134, v241
	ds_read_b64_tr_b16 v[88:89], v243 offset:54272
	ds_read_b64_tr_b16 v[90:91], v243 offset:54784
	global_load_lds_dwordx4 v224, s[4:5]
	s_add_u32 s4, s4, 0x20000
	s_addc_u32 s5, s5, 0
	s_waitcnt lgkmcnt(8)
	v_mfma_f32_32x32x16_bf16 v[0:15], v[168:171], v[92:95], v[0:15]
	v_mov_b32_e32 v135, v241
	v_mov_b32_e32 v136, v241
	v_mov_b32_e32 v137, v241
	v_mov_b32_e32 v138, v241
	v_mov_b32_e32 v139, v241
	v_mov_b32_e32 v140, v241
	v_mov_b32_e32 v141, v241
	v_mov_b32_e32 v142, v241
	v_mov_b32_e32 v143, v241
	v_max3_f32 v246, v112, v113, v114
	ds_read_b64_tr_b16 v[92:93], v243 offset:51200
	ds_read_b64_tr_b16 v[94:95], v243 offset:51712
	v_mfma_f32_32x32x16_bf16 v[16:31], v[168:171], v[96:99], v[16:31]
	v_max3_f32 v247, v115, v116, v117
	v_max3_f32 v246, v246, v118, v119
	v_max3_f32 v247, v247, v120, v121
	v_max3_f32 v246, v246, v122, v123
	v_max3_f32 v247, v247, v124, v125
	v_max3_f32 v246, v246, v126, v127
	v_max3_f32 v247, v247, v128, v129
	v_max3_f32 v246, v246, v130, v131
	v_max3_f32 v247, v247, v132, v133
	v_max3_f32 v246, v246, v134, v135
	ds_read_b64_tr_b16 v[96:97], v243 offset:55296
	ds_read_b64_tr_b16 v[98:99], v243 offset:55808
	v_mfma_f32_32x32x16_bf16 v[0:15], v[172:175], v[100:103], v[0:15]
	v_max3_f32 v247, v247, v136, v137
	v_max3_f32 v246, v246, v138, v139
	v_max3_f32 v247, v247, v140, v141
	v_max3_f32 v246, v246, v142, v143
	v_max_f32_e32 v248, v246, v247
	ds_read_b64_tr_b16 v[100:101], v243 offset:52224
	ds_read_b64_tr_b16 v[102:103], v243 offset:52736
	v_mfma_f32_32x32x16_bf16 v[16:31], v[172:175], v[104:107], v[16:31]
	ds_read_b64_tr_b16 v[104:105], v243 offset:56320
	ds_read_b64_tr_b16 v[106:107], v243 offset:56832
	s_waitcnt lgkmcnt(8)
	v_mfma_f32_32x32x16_bf16 v[32:47], v[160:163], v[214:217], v[32:47]
	ds_read_b128 v[176:179], v244 offset:0
	ds_read_b128 v[180:183], v244 offset:512
	v_cmp_lt_f32_e32 vcc, s87, v248
	s_cbranch_vccnz .Lat_rare_T3e

; __device__ __forceinline__ void cmask(f32x16&p0,f32x16&p1,int jb,int qrel,int hi){
;   const float NEG=-INFINITY; int kb=64*jb+4*hi;
;   #pragma unroll
;   for(int r=0;r<16;++r){int kv=kb+(r&3)+8*(r>>2); if(kv>qrel)p0[r]=NEG; if(kv+32>qrel)p1[r]=NEG;}
; }
.Lat_T3_o:
	v_add_u32_e32 v243, s16, v204
	ds_read_b64_tr_b16 v[214:215], v243 offset:24576
	ds_read_b64_tr_b16 v[216:217], v243 offset:25088
	v_mfma_f32_32x32x16_bf16 v[112:127], v[176:179], v[144:147], v[64:79]
	v_add_f32_e32 v245, v80, v81
	v_add_f32_e32 v246, v82, v83
	v_add_f32_e32 v245, v84, v245
	v_add_f32_e32 v246, v85, v246
	v_cvt_pk_bf16_f32 v160, v80, v81
	v_cvt_pk_bf16_f32 v161, v82, v83
	ds_read_b64_tr_b16 v[80:81], v243 offset:28672
	ds_read_b64_tr_b16 v[82:83], v243 offset:29184
	v_mfma_f32_32x32x16_bf16 v[128:143], v[180:183], v[144:147], v[64:79]
	v_add_f32_e32 v245, v86, v245
	v_add_f32_e32 v246, v87, v246
	v_add_f32_e32 v245, v88, v245
	v_add_f32_e32 v246, v89, v246
	v_cvt_pk_bf16_f32 v162, v84, v85
	v_cvt_pk_bf16_f32 v163, v86, v87
	ds_read_b64_tr_b16 v[84:85], v243 offset:25600
	ds_read_b64_tr_b16 v[86:87], v243 offset:26112
	v_mfma_f32_32x32x16_bf16 v[112:127], v[184:187], v[148:151], v[112:127]
	v_add_f32_e32 v245, v90, v245
	v_add_f32_e32 v246, v91, v246
	v_add_f32_e32 v245, v92, v245
	v_add_f32_e32 v246, v93, v246
	v_cvt_pk_bf16_f32 v164, v88, v89
	v_cvt_pk_bf16_f32 v165, v90, v91
	ds_read_b64_tr_b16 v[88:89], v243 offset:29696
	ds_read_b64_tr_b16 v[90:91], v243 offset:30208
	v_mfma_f32_32x32x16_bf16 v[128:143], v[188:191], v[148:151], v[128:143]
	v_add_f32_e32 v245, v94, v245
	v_add_f32_e32 v246, v95, v246
	v_add_f32_e32 v245, v96, v245
	v_add_f32_e32 v246, v97, v246
	v_cvt_pk_bf16_f32 v166, v92, v93
	v_cvt_pk_bf16_f32 v167, v94, v95
	ds_read_b64_tr_b16 v[92:93], v243 offset:26624
	ds_read_b64_tr_b16 v[94:95], v243 offset:27136
	v_mfma_f32_32x32x16_bf16 v[112:127], v[192:195], v[152:155], v[112:127]
	v_add_f32_e32 v245, v98, v245
	v_add_f32_e32 v246, v99, v246
	v_add_f32_e32 v245, v100, v245
	v_add_f32_e32 v246, v101, v246
	v_cvt_pk_bf16_f32 v168, v96, v97
	v_cvt_pk_bf16_f32 v169, v98, v99
	ds_read_b64_tr_b16 v[96:97], v243 offset:30720
	ds_read_b64_tr_b16 v[98:99], v243 offset:31232
	v_mfma_f32_32x32x16_bf16 v[128:143], v[196:199], v[152:155], v[128:143]
	v_add_f32_e32 v245, v102, v245
	v_add_f32_e32 v246, v103, v246
	v_add_f32_e32 v245, v104, v245
	v_add_f32_e32 v246, v105, v246
	v_cvt_pk_bf16_f32 v170, v100, v101
	v_cvt_pk_bf16_f32 v171, v102, v103
	ds_read_b64_tr_b16 v[100:101], v243 offset:27648
	ds_read_b64_tr_b16 v[102:103], v243 offset:28160
	v_mfma_f32_32x32x16_bf16 v[112:127], v[200:203], v[156:159], v[112:127]
	v_add_f32_e32 v245, v106, v245
	v_add_f32_e32 v246, v107, v246
	v_add_f32_e32 v245, v108, v245
	v_add_f32_e32 v246, v109, v246
	v_cvt_pk_bf16_f32 v172, v104, v105
	v_cvt_pk_bf16_f32 v173, v106, v107
	ds_read_b64_tr_b16 v[104:105], v243 offset:31744
	ds_read_b64_tr_b16 v[106:107], v243 offset:32256
	v_mfma_f32_32x32x16_bf16 v[128:143], v[206:209], v[156:159], v[128:143]
	v_add_f32_e32 v245, v110, v245
	v_add_f32_e32 v246, v111, v246
	v_add_f32_e32 v245, v245, v246
	v_cvt_pk_bf16_f32 v174, v108, v109
	v_cvt_pk_bf16_f32 v175, v110, v111
	v_add_f32_e32 v211, v211, v245
	v_add_u32_e32 v244, s18, v219
	s_waitcnt lgkmcnt(8)
	v_mfma_f32_32x32x16_bf16 v[0:15], v[160:163], v[214:217], v[0:15]
	v_add_u32_e32 v242, 0xffffffc0, v225
	v_cmp_gt_i32_e64 s[28:29], 32, v242
	v_cmp_gt_i32_e64 s[30:31], 33, v242
	v_cmp_gt_i32_e64 s[34:35], 34, v242
	v_cndmask_b32_e64 v128, v128, v241, s[28:29]
	v_cmp_gt_i32_e64 s[28:29], 35, v242
	v_cndmask_b32_e64 v129, v129, v241, s[30:31]
	v_cmp_gt_i32_e64 s[30:31], 40, v242
	v_cndmask_b32_e64 v130, v130, v241, s[34:35]
	v_cmp_gt_i32_e64 s[34:35], 41, v242
	ds_read_b64_tr_b16 v[214:215], v243 offset:49152
	ds_read_b64_tr_b16 v[216:217], v243 offset:49664
	v_mfma_f32_32x32x16_bf16 v[16:31], v[160:163], v[80:83], v[16:31]
	v_cndmask_b32_e64 v131, v131, v241, s[28:29]
	v_cmp_gt_i32_e64 s[28:29], 42, v242
	v_cndmask_b32_e64 v132, v132, v241, s[30:31]
	v_cmp_gt_i32_e64 s[30:31], 43, v242
	v_cndmask_b32_e64 v133, v133, v241, s[34:35]
	v_cmp_gt_i32_e64 s[34:35], 48, v242
	v_cndmask_b32_e64 v134, v134, v241, s[28:29]
	v_cmp_gt_i32_e64 s[28:29], 49, v242
	v_cndmask_b32_e64 v135, v135, v241, s[30:31]
	v_cmp_gt_i32_e64 s[30:31], 50, v242
	ds_read_b64_tr_b16 v[80:81], v243 offset:53248
	ds_read_b64_tr_b16 v[82:83], v243 offset:53760
	v_mfma_f32_32x32x16_bf16 v[0:15], v[164:167], v[84:87], v[0:15]
	s_add_i32 s21, s18, s54
	s_add_i32 m0, s21, 0x6000
	v_cndmask_b32_e64 v136, v136, v241, s[34:35]
	v_cmp_gt_i32_e64 s[34:35], 51, v242
	v_cndmask_b32_e64 v137, v137, v241, s[28:29]
	v_cmp_gt_i32_e64 s[28:29], 56, v242
	v_cndmask_b32_e64 v138, v138, v241, s[30:31]
	v_cmp_gt_i32_e64 s[30:31], 57, v242
	v_cndmask_b32_e64 v139, v139, v241, s[34:35]
	v_cmp_gt_i32_e64 s[34:35], 58, v242
	v_cndmask_b32_e64 v140, v140, v241, s[28:29]
	v_cmp_gt_i32_e64 s[28:29], 59, v242
	ds_read_b64_tr_b16 v[84:85], v243 offset:50176
	ds_read_b64_tr_b16 v[86:87], v243 offset:50688
	global_load_lds_dwordx4 v223, s[4:5]
	v_mfma_f32_32x32x16_bf16 v[16:31], v[164:167], v[88:91], v[16:31]
	s_add_i32 m0, s21, 0xc000
	v_cndmask_b32_e64 v141, v141, v241, s[30:31]
	v_cndmask_b32_e64 v142, v142, v241, s[34:35]
	v_cndmask_b32_e64 v143, v143, v241, s[28:29]
	v_max3_f32 v246, v112, v113, v114
	v_max3_f32 v247, v115, v116, v117
	v_max3_f32 v246, v246, v118, v119
	v_max3_f32 v247, v247, v120, v121
	v_max3_f32 v246, v246, v122, v123
	v_max3_f32 v247, v247, v124, v125
	v_max3_f32 v246, v246, v126, v127
	ds_read_b64_tr_b16 v[88:89], v243 offset:54272
	ds_read_b64_tr_b16 v[90:91], v243 offset:54784
	global_load_lds_dwordx4 v224, s[4:5]
	s_add_u32 s4, s4, 0x20000
	s_addc_u32 s5, s5, 0
	s_waitcnt lgkmcnt(8)
	v_mfma_f32_32x32x16_bf16 v[0:15], v[168:171], v[92:95], v[0:15]
	v_max3_f32 v247, v247, v128, v129
	v_max3_f32 v246, v246, v130, v131
	v_max3_f32 v247, v247, v132, v133
	v_max3_f32 v246, v246, v134, v135
	v_max3_f32 v247, v247, v136, v137
	v_max3_f32 v246, v246, v138, v139
	v_max3_f32 v247, v247, v140, v141
	v_max3_f32 v246, v246, v142, v143
	v_max_f32_e32 v248, v246, v247
	ds_read_b64_tr_b16 v[92:93], v243 offset:51200
	ds_read_b64_tr_b16 v[94:95], v243 offset:51712
	v_mfma_f32_32x32x16_bf16 v[16:31], v[168:171], v[96:99], v[16:31]
	ds_read_b64_tr_b16 v[96:97], v243 offset:55296
	ds_read_b64_tr_b16 v[98:99], v243 offset:55808
	v_mfma_f32_32x32x16_bf16 v[0:15], v[172:175], v[100:103], v[0:15]
	ds_read_b64_tr_b16 v[100:101], v243 offset:52224
	ds_read_b64_tr_b16 v[102:103], v243 offset:52736
	v_mfma_f32_32x32x16_bf16 v[16:31], v[172:175], v[104:107], v[16:31]
	ds_read_b64_tr_b16 v[104:105], v243 offset:56320
	ds_read_b64_tr_b16 v[106:107], v243 offset:56832
	s_waitcnt lgkmcnt(8)
	v_mfma_f32_32x32x16_bf16 v[32:47], v[160:163], v[214:217], v[32:47]
	ds_read_b128 v[176:179], v244 offset:0
	ds_read_b128 v[180:183], v244 offset:512
	v_cmp_lt_f32_e32 vcc, s87, v248
	s_cbranch_vccnz .Lat_rare_T3o

.Lat_T3_u:
	v_add_u32_e32 v243, s16, v204
	ds_read_b64_tr_b16 v[214:215], v243 offset:24576
	ds_read_b64_tr_b16 v[216:217], v243 offset:25088
	v_mfma_f32_32x32x16_bf16 v[112:127], v[176:179], v[144:147], v[64:79]
	v_add_f32_e32 v245, v80, v81
	v_add_f32_e32 v246, v82, v83
	v_add_f32_e32 v245, v84, v245
	v_add_f32_e32 v246, v85, v246
	v_cvt_pk_bf16_f32 v160, v80, v81
	v_cvt_pk_bf16_f32 v161, v82, v83
	ds_read_b64_tr_b16 v[80:81], v243 offset:28672
	ds_read_b64_tr_b16 v[82:83], v243 offset:29184
	v_mfma_f32_32x32x16_bf16 v[128:143], v[180:183], v[144:147], v[64:79]
	v_add_f32_e32 v245, v86, v245
	v_add_f32_e32 v246, v87, v246
	v_add_f32_e32 v245, v88, v245
	v_add_f32_e32 v246, v89, v246
	v_cvt_pk_bf16_f32 v162, v84, v85
	v_cvt_pk_bf16_f32 v163, v86, v87
	ds_read_b64_tr_b16 v[84:85], v243 offset:25600
	ds_read_b64_tr_b16 v[86:87], v243 offset:26112
	v_mfma_f32_32x32x16_bf16 v[112:127], v[184:187], v[148:151], v[112:127]
	v_add_f32_e32 v245, v90, v245
	v_add_f32_e32 v246, v91, v246
	v_add_f32_e32 v245, v92, v245
	v_add_f32_e32 v246, v93, v246
	v_cvt_pk_bf16_f32 v164, v88, v89
	v_cvt_pk_bf16_f32 v165, v90, v91
	ds_read_b64_tr_b16 v[88:89], v243 offset:29696
	ds_read_b64_tr_b16 v[90:91], v243 offset:30208
	v_mfma_f32_32x32x16_bf16 v[128:143], v[188:191], v[148:151], v[128:143]
	v_add_f32_e32 v245, v94, v245
	v_add_f32_e32 v246, v95, v246
	v_add_f32_e32 v245, v96, v245
	v_add_f32_e32 v246, v97, v246
	v_cvt_pk_bf16_f32 v166, v92, v93
	v_cvt_pk_bf16_f32 v167, v94, v95
	ds_read_b64_tr_b16 v[92:93], v243 offset:26624
	ds_read_b64_tr_b16 v[94:95], v243 offset:27136
	v_mfma_f32_32x32x16_bf16 v[112:127], v[192:195], v[152:155], v[112:127]
	v_add_f32_e32 v245, v98, v245
	v_add_f32_e32 v246, v99, v246
	v_add_f32_e32 v245, v100, v245
	v_add_f32_e32 v246, v101, v246
	v_cvt_pk_bf16_f32 v168, v96, v97
	v_cvt_pk_bf16_f32 v169, v98, v99
	ds_read_b64_tr_b16 v[96:97], v243 offset:30720
	ds_read_b64_tr_b16 v[98:99], v243 offset:31232
	v_mfma_f32_32x32x16_bf16 v[128:143], v[196:199], v[152:155], v[128:143]
	v_add_f32_e32 v245, v102, v245
	v_add_f32_e32 v246, v103, v246
	v_add_f32_e32 v245, v104, v245
	v_add_f32_e32 v246, v105, v246
	v_cvt_pk_bf16_f32 v170, v100, v101
	v_cvt_pk_bf16_f32 v171, v102, v103
	ds_read_b64_tr_b16 v[100:101], v243 offset:27648
	ds_read_b64_tr_b16 v[102:103], v243 offset:28160
	v_mfma_f32_32x32x16_bf16 v[112:127], v[200:203], v[156:159], v[112:127]
	v_add_f32_e32 v245, v106, v245
	v_add_f32_e32 v246, v107, v246
	v_add_f32_e32 v245, v108, v245
	v_add_f32_e32 v246, v109, v246
	v_cvt_pk_bf16_f32 v172, v104, v105
	v_cvt_pk_bf16_f32 v173, v106, v107
	ds_read_b64_tr_b16 v[104:105], v243 offset:31744
	ds_read_b64_tr_b16 v[106:107], v243 offset:32256
	v_mfma_f32_32x32x16_bf16 v[128:143], v[206:209], v[156:159], v[128:143]
	v_add_f32_e32 v245, v110, v245
	v_add_f32_e32 v246, v111, v246
	v_add_f32_e32 v245, v245, v246
	v_cvt_pk_bf16_f32 v174, v108, v109
	v_cvt_pk_bf16_f32 v175, v110, v111
	v_add_f32_e32 v211, v211, v245
	v_add_u32_e32 v244, s18, v219
	s_waitcnt lgkmcnt(8)
	v_mfma_f32_32x32x16_bf16 v[0:15], v[160:163], v[214:217], v[0:15]
	v_max3_f32 v246, v112, v113, v114
	v_max3_f32 v247, v115, v116, v117
	ds_read_b64_tr_b16 v[214:215], v243 offset:49152
	ds_read_b64_tr_b16 v[216:217], v243 offset:49664
	v_mfma_f32_32x32x16_bf16 v[16:31], v[160:163], v[80:83], v[16:31]
	v_max3_f32 v246, v246, v118, v119
	v_max3_f32 v247, v247, v120, v121
	v_max3_f32 v246, v246, v122, v123
	v_max3_f32 v247, v247, v124, v125
	ds_read_b64_tr_b16 v[80:81], v243 offset:53248
	ds_read_b64_tr_b16 v[82:83], v243 offset:53760
	v_mfma_f32_32x32x16_bf16 v[0:15], v[164:167], v[84:87], v[0:15]
	s_add_i32 s21, s18, s54
	s_add_i32 m0, s21, 0x6000
	v_max3_f32 v246, v246, v126, v127
	v_max3_f32 v247, v247, v128, v129
	v_max3_f32 v246, v246, v130, v131
	v_max3_f32 v247, v247, v132, v133
	ds_read_b64_tr_b16 v[84:85], v243 offset:50176
	ds_read_b64_tr_b16 v[86:87], v243 offset:50688
	global_load_lds_dwordx4 v223, s[4:5]
	v_mfma_f32_32x32x16_bf16 v[16:31], v[164:167], v[88:91], v[16:31]
	s_add_i32 m0, s21, 0xc000
	v_max3_f32 v246, v246, v134, v135
	v_max3_f32 v247, v247, v136, v137
	v_max3_f32 v246, v246, v138, v139
	v_max3_f32 v247, v247, v140, v141
	ds_read_b64_tr_b16 v[88:89], v243 offset:54272
	ds_read_b64_tr_b16 v[90:91], v243 offset:54784
	global_load_lds_dwordx4 v224, s[4:5]
	s_add_u32 s4, s4, 0x20000
	s_addc_u32 s5, s5, 0
	s_waitcnt lgkmcnt(8)
	v_mfma_f32_32x32x16_bf16 v[0:15], v[168:171], v[92:95], v[0:15]
	v_max3_f32 v246, v246, v142, v143
	v_max_f32_e32 v248, v246, v247
	ds_read_b64_tr_b16 v[92:93], v243 offset:51200
	ds_read_b64_tr_b16 v[94:95], v243 offset:51712
	v_cmp_lt_f32_e32 vcc, s87, v248
	s_cbranch_vccnz .Lat_rare_T3u
.Lat_cont_T3u:
	v_mfma_f32_32x32x16_bf16 v[16:31], v[168:171], v[96:99], v[16:31]
	v_exp_f32_e32 v112, v112
	v_exp_f32_e32 v113, v113
	v_exp_f32_e32 v114, v114
	ds_read_b64_tr_b16 v[96:97], v243 offset:55296
	ds_read_b64_tr_b16 v[98:99], v243 offset:55808
	v_mfma_f32_32x32x16_bf16 v[0:15], v[172:175], v[100:103], v[0:15]
	v_exp_f32_e32 v115, v115
	v_exp_f32_e32 v116, v116
	v_exp_f32_e32 v117, v117
	ds_read_b64_tr_b16 v[100:101], v243 offset:52224
	ds_read_b64_tr_b16 v[102:103], v243 offset:52736
	v_mfma_f32_32x32x16_bf16 v[16:31], v[172:175], v[104:107], v[16:31]
	v_exp_f32_e32 v118, v118
	v_exp_f32_e32 v119, v119
	v_exp_f32_e32 v120, v120
	ds_read_b64_tr_b16 v[104:105], v243 offset:56320
	ds_read_b64_tr_b16 v[106:107], v243 offset:56832
	s_waitcnt lgkmcnt(8)
	v_mfma_f32_32x32x16_bf16 v[32:47], v[160:163], v[214:217], v[32:47]
	v_exp_f32_e32 v121, v121
	v_exp_f32_e32 v122, v122
	v_exp_f32_e32 v123, v123
	ds_read_b128 v[176:179], v244 offset:0
	ds_read_b128 v[180:183], v244 offset:512
	v_mfma_f32_32x32x16_bf16 v[48:63], v[160:163], v[80:83], v[48:63]
	v_exp_f32_e32 v124, v124
	v_exp_f32_e32 v125, v125
	v_exp_f32_e32 v126, v126
	ds_read_b128 v[184:187], v244 offset:2048
	ds_read_b128 v[188:191], v244 offset:2560
	v_mfma_f32_32x32x16_bf16 v[32:47], v[164:167], v[84:87], v[32:47]
	v_exp_f32_e32 v127, v127
	v_exp_f32_e32 v128, v128
	v_exp_f32_e32 v129, v129
	ds_read_b128 v[192:195], v244 offset:4096
	ds_read_b128 v[196:199], v244 offset:4608
	v_mfma_f32_32x32x16_bf16 v[48:63], v[164:167], v[88:91], v[48:63]
	v_exp_f32_e32 v130, v130
	v_exp_f32_e32 v131, v131
	v_exp_f32_e32 v132, v132
	ds_read_b128 v[200:203], v244 offset:6144
	ds_read_b128 v[206:209], v244 offset:6656
	s_waitcnt lgkmcnt(8)
	v_mfma_f32_32x32x16_bf16 v[32:47], v[168:171], v[92:95], v[32:47]
	v_exp_f32_e32 v133, v133
	v_exp_f32_e32 v134, v134
	v_exp_f32_e32 v135, v135
	v_mfma_f32_32x32x16_bf16 v[48:63], v[168:171], v[96:99], v[48:63]
	v_exp_f32_e32 v136, v136
	v_exp_f32_e32 v137, v137
	v_exp_f32_e32 v138, v138
	v_mfma_f32_32x32x16_bf16 v[32:47], v[172:175], v[100:103], v[32:47]
	v_exp_f32_e32 v139, v139
	v_exp_f32_e32 v140, v140
	v_exp_f32_e32 v141, v141
	v_mfma_f32_32x32x16_bf16 v[48:63], v[172:175], v[104:107], v[48:63]
	v_exp_f32_e32 v142, v142
	v_exp_f32_e32 v143, v143
	s_waitcnt vmcnt(2) lgkmcnt(0)
	s_barrier
	s_cbranch_vccnz .Lat_resc_T3u

.Lat_T3_end:
.Lat_step_T2:
	s_cmp_lt_u32 s55, 2
	s_cbranch_scc1 .Lat_T2_light
	s_cmp_eq_u32 s55, 2
	s_cbranch_scc0 .Lat_T2_u
	s_bitcmp1_b32 s46, 5
	s_cbranch_scc1 .Lat_T2_o
	v_add_u32_e32 v243, s16, v204
	ds_read_b64_tr_b16 v[214:215], v243 offset:24576
	ds_read_b64_tr_b16 v[216:217], v243 offset:25088
	v_mfma_f32_32x32x16_bf16 v[80:95], v[176:179], v[144:147], v[64:79]
	v_add_f32_e32 v245, v112, v113
	v_add_f32_e32 v246, v114, v115
	v_add_f32_e32 v245, v116, v245
	v_add_f32_e32 v246, v117, v246
	v_cvt_pk_bf16_f32 v160, v112, v113
	v_cvt_pk_bf16_f32 v161, v114, v115
	ds_read_b64_tr_b16 v[112:113], v243 offset:28672
	ds_read_b64_tr_b16 v[114:115], v243 offset:29184
	v_mfma_f32_32x32x16_bf16 v[96:111], v[180:183], v[144:147], v[64:79]
	v_add_f32_e32 v245, v118, v245
	v_add_f32_e32 v246, v119, v246
	v_add_f32_e32 v245, v120, v245
	v_add_f32_e32 v246, v121, v246
	v_cvt_pk_bf16_f32 v162, v116, v117
	v_cvt_pk_bf16_f32 v163, v118, v119
	ds_read_b64_tr_b16 v[116:117], v243 offset:25600
	ds_read_b64_tr_b16 v[118:119], v243 offset:26112
	v_mfma_f32_32x32x16_bf16 v[80:95], v[184:187], v[148:151], v[80:95]
	v_add_f32_e32 v245, v122, v245
	v_add_f32_e32 v246, v123, v246
	v_add_f32_e32 v245, v124, v245
	v_add_f32_e32 v246, v125, v246
	v_cvt_pk_bf16_f32 v164, v120, v121
	v_cvt_pk_bf16_f32 v165, v122, v123
	ds_read_b64_tr_b16 v[120:121], v243 offset:29696
	ds_read_b64_tr_b16 v[122:123], v243 offset:30208
	v_mfma_f32_32x32x16_bf16 v[96:111], v[188:191], v[148:151], v[96:111]
	v_add_f32_e32 v245, v126, v245
	v_add_f32_e32 v246, v127, v246
	v_add_f32_e32 v245, v128, v245
	v_add_f32_e32 v246, v129, v246
	v_cvt_pk_bf16_f32 v166, v124, v125
	v_cvt_pk_bf16_f32 v167, v126, v127
	ds_read_b64_tr_b16 v[124:125], v243 offset:26624
	ds_read_b64_tr_b16 v[126:127], v243 offset:27136
	v_mfma_f32_32x32x16_bf16 v[80:95], v[192:195], v[152:155], v[80:95]
	v_add_f32_e32 v245, v130, v245
	v_add_f32_e32 v246, v131, v246
	v_add_f32_e32 v245, v132, v245
	v_add_f32_e32 v246, v133, v246
	v_cvt_pk_bf16_f32 v168, v128, v129
	v_cvt_pk_bf16_f32 v169, v130, v131
	ds_read_b64_tr_b16 v[128:129], v243 offset:30720
	ds_read_b64_tr_b16 v[130:131], v243 offset:31232
	v_mfma_f32_32x32x16_bf16 v[96:111], v[196:199], v[152:155], v[96:111]
	v_add_f32_e32 v245, v134, v245
	v_add_f32_e32 v246, v135, v246
	v_add_f32_e32 v245, v136, v245
	v_add_f32_e32 v246, v137, v246
	v_cvt_pk_bf16_f32 v170, v132, v133
	v_cvt_pk_bf16_f32 v171, v134, v135
	ds_read_b64_tr_b16 v[132:133], v243 offset:27648
	ds_read_b64_tr_b16 v[134:135], v243 offset:28160
	v_mfma_f32_32x32x16_bf16 v[80:95], v[200:203], v[156:159], v[80:95]
	v_add_f32_e32 v245, v138, v245
	v_add_f32_e32 v246, v139, v246
	v_add_f32_e32 v245, v140, v245
	v_add_f32_e32 v246, v141, v246
	v_cvt_pk_bf16_f32 v172, v136, v137
	v_cvt_pk_bf16_f32 v173, v138, v139
	ds_read_b64_tr_b16 v[136:137], v243 offset:31744
	ds_read_b64_tr_b16 v[138:139], v243 offset:32256
	v_mfma_f32_32x32x16_bf16 v[96:111], v[206:209], v[156:159], v[96:111]
	v_add_f32_e32 v245, v142, v245
	v_add_f32_e32 v246, v143, v246
	v_add_f32_e32 v245, v245, v246
	v_cvt_pk_bf16_f32 v174, v140, v141
	v_cvt_pk_bf16_f32 v175, v142, v143
	v_add_f32_e32 v211, v211, v245
	v_add_u32_e32 v244, s18, v219
	s_waitcnt lgkmcnt(8)
; __device__ __forceinline__ void cmask(f32x16&p0,f32x16&p1,int jb,int qrel,int hi){
;   const float NEG=-INFINITY; int kb=64*jb+4*hi;
;   #pragma unroll
;   for(int r=0;r<16;++r){int kv=kb+(r&3)+8*(r>>2); if(kv>qrel)p0[r]=NEG; if(kv+32>qrel)p1[r]=NEG;}
; }
	v_mfma_f32_32x32x16_bf16 v[0:15], v[160:163], v[214:217], v[0:15]
	v_add_u32_e32 v242, 0xffffff80, v225
	v_cmp_gt_i32_e64 s[28:29], 0, v242
	v_cmp_gt_i32_e64 s[30:31], 1, v242
	v_cmp_gt_i32_e64 s[34:35], 2, v242
	v_cndmask_b32_e64 v80, v80, v241, s[28:29]
	v_cmp_gt_i32_e64 s[28:29], 3, v242
	v_cndmask_b32_e64 v81, v81, v241, s[30:31]
	v_cmp_gt_i32_e64 s[30:31], 8, v242
	v_cndmask_b32_e64 v82, v82, v241, s[34:35]
	v_cmp_gt_i32_e64 s[34:35], 9, v242
	ds_read_b64_tr_b16 v[214:215], v243 offset:49152
	ds_read_b64_tr_b16 v[216:217], v243 offset:49664
	v_mfma_f32_32x32x16_bf16 v[16:31], v[160:163], v[112:115], v[16:31]
	v_cndmask_b32_e64 v83, v83, v241, s[28:29]
	v_cmp_gt_i32_e64 s[28:29], 10, v242
	v_cndmask_b32_e64 v84, v84, v241, s[30:31]
	v_cmp_gt_i32_e64 s[30:31], 11, v242
	v_cndmask_b32_e64 v85, v85, v241, s[34:35]
	v_cmp_gt_i32_e64 s[34:35], 16, v242
	v_cndmask_b32_e64 v86, v86, v241, s[28:29]
	v_cmp_gt_i32_e64 s[28:29], 17, v242
	v_cndmask_b32_e64 v87, v87, v241, s[30:31]
	v_cmp_gt_i32_e64 s[30:31], 18, v242
	ds_read_b64_tr_b16 v[112:113], v243 offset:53248
	ds_read_b64_tr_b16 v[114:115], v243 offset:53760
	v_mfma_f32_32x32x16_bf16 v[0:15], v[164:167], v[116:119], v[0:15]
	s_add_i32 s21, s18, s54
	s_add_i32 m0, s21, 0x6000
	v_cndmask_b32_e64 v88, v88, v241, s[34:35]
	v_cmp_gt_i32_e64 s[34:35], 19, v242
	v_cndmask_b32_e64 v89, v89, v241, s[28:29]
	v_cmp_gt_i32_e64 s[28:29], 24, v242
	v_cndmask_b32_e64 v90, v90, v241, s[30:31]
	v_cmp_gt_i32_e64 s[30:31], 25, v242
	v_cndmask_b32_e64 v91, v91, v241, s[34:35]
	v_cmp_gt_i32_e64 s[34:35], 26, v242
	v_cndmask_b32_e64 v92, v92, v241, s[28:29]
	v_cmp_gt_i32_e64 s[28:29], 27, v242
	ds_read_b64_tr_b16 v[116:117], v243 offset:50176
	ds_read_b64_tr_b16 v[118:119], v243 offset:50688
	global_load_lds_dwordx4 v223, s[4:5]
	v_mfma_f32_32x32x16_bf16 v[16:31], v[164:167], v[120:123], v[16:31]
	s_add_i32 m0, s21, 0xc000
	v_cndmask_b32_e64 v93, v93, v241, s[30:31]
	v_cndmask_b32_e64 v94, v94, v241, s[34:35]
	v_cndmask_b32_e64 v95, v95, v241, s[28:29]
	v_mov_b32_e32 v96, v241
	v_mov_b32_e32 v97, v241
	v_mov_b32_e32 v98, v241
	v_mov_b32_e32 v99, v241
	v_mov_b32_e32 v100, v241
	v_mov_b32_e32 v101, v241
	v_mov_b32_e32 v102, v241
	ds_read_b64_tr_b16 v[120:121], v243 offset:54272
	ds_read_b64_tr_b16 v[122:123], v243 offset:54784
	global_load_lds_dwordx4 v224, s[4:5]
	s_add_u32 s4, s4, 0x20000
	s_addc_u32 s5, s5, 0
	s_waitcnt lgkmcnt(8)
	v_mfma_f32_32x32x16_bf16 v[0:15], v[168:171], v[124:127], v[0:15]
	v_mov_b32_e32 v103, v241
	v_mov_b32_e32 v104, v241
	v_mov_b32_e32 v105, v241
	v_mov_b32_e32 v106, v241
	v_mov_b32_e32 v107, v241
	v_mov_b32_e32 v108, v241
	v_mov_b32_e32 v109, v241
	v_mov_b32_e32 v110, v241
	v_mov_b32_e32 v111, v241
	v_max3_f32 v246, v80, v81, v82
	ds_read_b64_tr_b16 v[124:125], v243 offset:51200
	ds_read_b64_tr_b16 v[126:127], v243 offset:51712
	v_mfma_f32_32x32x16_bf16 v[16:31], v[168:171], v[128:131], v[16:31]
	v_max3_f32 v247, v83, v84, v85
	v_max3_f32 v246, v246, v86, v87
	v_max3_f32 v247, v247, v88, v89
	v_max3_f32 v246, v246, v90, v91
	v_max3_f32 v247, v247, v92, v93
	v_max3_f32 v246, v246, v94, v95
	v_max3_f32 v247, v247, v96, v97
	v_max3_f32 v246, v246, v98, v99
	v_max3_f32 v247, v247, v100, v101
	v_max3_f32 v246, v246, v102, v103
	ds_read_b64_tr_b16 v[128:129], v243 offset:55296
	ds_read_b64_tr_b16 v[130:131], v243 offset:55808
	v_mfma_f32_32x32x16_bf16 v[0:15], v[172:175], v[132:135], v[0:15]
	v_max3_f32 v247, v247, v104, v105
	v_max3_f32 v246, v246, v106, v107
	v_max3_f32 v247, v247, v108, v109
	v_max3_f32 v246, v246, v110, v111
	v_max_f32_e32 v248, v246, v247
	ds_read_b64_tr_b16 v[132:133], v243 offset:52224
	ds_read_b64_tr_b16 v[134:135], v243 offset:52736
	v_mfma_f32_32x32x16_bf16 v[16:31], v[172:175], v[136:139], v[16:31]
	ds_read_b64_tr_b16 v[136:137], v243 offset:56320
	ds_read_b64_tr_b16 v[138:139], v243 offset:56832
	s_waitcnt lgkmcnt(8)
	v_mfma_f32_32x32x16_bf16 v[32:47], v[160:163], v[214:217], v[32:47]
	ds_read_b128 v[176:179], v244 offset:0
	ds_read_b128 v[180:183], v244 offset:512
	v_cmp_lt_f32_e32 vcc, s87, v248
	s_cbranch_vccnz .Lat_rare_T2e

; __device__ __forceinline__ void cmask(f32x16&p0,f32x16&p1,int jb,int qrel,int hi){
;   const float NEG=-INFINITY; int kb=64*jb+4*hi;
;   #pragma unroll
;   for(int r=0;r<16;++r){int kv=kb+(r&3)+8*(r>>2); if(kv>qrel)p0[r]=NEG; if(kv+32>qrel)p1[r]=NEG;}
; }
.Lat_T2_o:
	v_add_u32_e32 v243, s16, v204
	ds_read_b64_tr_b16 v[214:215], v243 offset:24576
	ds_read_b64_tr_b16 v[216:217], v243 offset:25088
	v_mfma_f32_32x32x16_bf16 v[80:95], v[176:179], v[144:147], v[64:79]
	v_add_f32_e32 v245, v112, v113
	v_add_f32_e32 v246, v114, v115
	v_add_f32_e32 v245, v116, v245
	v_add_f32_e32 v246, v117, v246
	v_cvt_pk_bf16_f32 v160, v112, v113
	v_cvt_pk_bf16_f32 v161, v114, v115
	ds_read_b64_tr_b16 v[112:113], v243 offset:28672
	ds_read_b64_tr_b16 v[114:115], v243 offset:29184
	v_mfma_f32_32x32x16_bf16 v[96:111], v[180:183], v[144:147], v[64:79]
	v_add_f32_e32 v245, v118, v245
	v_add_f32_e32 v246, v119, v246
	v_add_f32_e32 v245, v120, v245
	v_add_f32_e32 v246, v121, v246
	v_cvt_pk_bf16_f32 v162, v116, v117
	v_cvt_pk_bf16_f32 v163, v118, v119
	ds_read_b64_tr_b16 v[116:117], v243 offset:25600
	ds_read_b64_tr_b16 v[118:119], v243 offset:26112
	v_mfma_f32_32x32x16_bf16 v[80:95], v[184:187], v[148:151], v[80:95]
	v_add_f32_e32 v245, v122, v245
	v_add_f32_e32 v246, v123, v246
	v_add_f32_e32 v245, v124, v245
	v_add_f32_e32 v246, v125, v246
	v_cvt_pk_bf16_f32 v164, v120, v121
	v_cvt_pk_bf16_f32 v165, v122, v123
	ds_read_b64_tr_b16 v[120:121], v243 offset:29696
	ds_read_b64_tr_b16 v[122:123], v243 offset:30208
	v_mfma_f32_32x32x16_bf16 v[96:111], v[188:191], v[148:151], v[96:111]
	v_add_f32_e32 v245, v126, v245
	v_add_f32_e32 v246, v127, v246
	v_add_f32_e32 v245, v128, v245
	v_add_f32_e32 v246, v129, v246
	v_cvt_pk_bf16_f32 v166, v124, v125
	v_cvt_pk_bf16_f32 v167, v126, v127
	ds_read_b64_tr_b16 v[124:125], v243 offset:26624
	ds_read_b64_tr_b16 v[126:127], v243 offset:27136
	v_mfma_f32_32x32x16_bf16 v[80:95], v[192:195], v[152:155], v[80:95]
	v_add_f32_e32 v245, v130, v245
	v_add_f32_e32 v246, v131, v246
	v_add_f32_e32 v245, v132, v245
	v_add_f32_e32 v246, v133, v246
	v_cvt_pk_bf16_f32 v168, v128, v129
	v_cvt_pk_bf16_f32 v169, v130, v131
	ds_read_b64_tr_b16 v[128:129], v243 offset:30720
	ds_read_b64_tr_b16 v[130:131], v243 offset:31232
	v_mfma_f32_32x32x16_bf16 v[96:111], v[196:199], v[152:155], v[96:111]
	v_add_f32_e32 v245, v134, v245
	v_add_f32_e32 v246, v135, v246
	v_add_f32_e32 v245, v136, v245
	v_add_f32_e32 v246, v137, v246
	v_cvt_pk_bf16_f32 v170, v132, v133
	v_cvt_pk_bf16_f32 v171, v134, v135
	ds_read_b64_tr_b16 v[132:133], v243 offset:27648
	ds_read_b64_tr_b16 v[134:135], v243 offset:28160
	v_mfma_f32_32x32x16_bf16 v[80:95], v[200:203], v[156:159], v[80:95]
	v_add_f32_e32 v245, v138, v245
	v_add_f32_e32 v246, v139, v246
	v_add_f32_e32 v245, v140, v245
	v_add_f32_e32 v246, v141, v246
	v_cvt_pk_bf16_f32 v172, v136, v137
	v_cvt_pk_bf16_f32 v173, v138, v139
	ds_read_b64_tr_b16 v[136:137], v243 offset:31744
	ds_read_b64_tr_b16 v[138:139], v243 offset:32256
	v_mfma_f32_32x32x16_bf16 v[96:111], v[206:209], v[156:159], v[96:111]
	v_add_f32_e32 v245, v142, v245
	v_add_f32_e32 v246, v143, v246
	v_add_f32_e32 v245, v245, v246
	v_cvt_pk_bf16_f32 v174, v140, v141
	v_cvt_pk_bf16_f32 v175, v142, v143
	v_add_f32_e32 v211, v211, v245
	v_add_u32_e32 v244, s18, v219
	s_waitcnt lgkmcnt(8)
	v_mfma_f32_32x32x16_bf16 v[0:15], v[160:163], v[214:217], v[0:15]
	v_add_u32_e32 v242, 0xffffff80, v225
	v_cmp_gt_i32_e64 s[28:29], 32, v242
	v_cmp_gt_i32_e64 s[30:31], 33, v242
	v_cmp_gt_i32_e64 s[34:35], 34, v242
	v_cndmask_b32_e64 v96, v96, v241, s[28:29]
	v_cmp_gt_i32_e64 s[28:29], 35, v242
	v_cndmask_b32_e64 v97, v97, v241, s[30:31]
	v_cmp_gt_i32_e64 s[30:31], 40, v242
	v_cndmask_b32_e64 v98, v98, v241, s[34:35]
	v_cmp_gt_i32_e64 s[34:35], 41, v242
	ds_read_b64_tr_b16 v[214:215], v243 offset:49152
	ds_read_b64_tr_b16 v[216:217], v243 offset:49664
	v_mfma_f32_32x32x16_bf16 v[16:31], v[160:163], v[112:115], v[16:31]
	v_cndmask_b32_e64 v99, v99, v241, s[28:29]
	v_cmp_gt_i32_e64 s[28:29], 42, v242
	v_cndmask_b32_e64 v100, v100, v241, s[30:31]
	v_cmp_gt_i32_e64 s[30:31], 43, v242
	v_cndmask_b32_e64 v101, v101, v241, s[34:35]
	v_cmp_gt_i32_e64 s[34:35], 48, v242
	v_cndmask_b32_e64 v102, v102, v241, s[28:29]
	v_cmp_gt_i32_e64 s[28:29], 49, v242
	v_cndmask_b32_e64 v103, v103, v241, s[30:31]
	v_cmp_gt_i32_e64 s[30:31], 50, v242
	ds_read_b64_tr_b16 v[112:113], v243 offset:53248
	ds_read_b64_tr_b16 v[114:115], v243 offset:53760
	v_mfma_f32_32x32x16_bf16 v[0:15], v[164:167], v[116:119], v[0:15]
	s_add_i32 s21, s18, s54
	s_add_i32 m0, s21, 0x6000
	v_cndmask_b32_e64 v104, v104, v241, s[34:35]
	v_cmp_gt_i32_e64 s[34:35], 51, v242
	v_cndmask_b32_e64 v105, v105, v241, s[28:29]
	v_cmp_gt_i32_e64 s[28:29], 56, v242
	v_cndmask_b32_e64 v106, v106, v241, s[30:31]
	v_cmp_gt_i32_e64 s[30:31], 57, v242
	v_cndmask_b32_e64 v107, v107, v241, s[34:35]
	v_cmp_gt_i32_e64 s[34:35], 58, v242
	v_cndmask_b32_e64 v108, v108, v241, s[28:29]
	v_cmp_gt_i32_e64 s[28:29], 59, v242
	ds_read_b64_tr_b16 v[116:117], v243 offset:50176
	ds_read_b64_tr_b16 v[118:119], v243 offset:50688
	global_load_lds_dwordx4 v223, s[4:5]
	v_mfma_f32_32x32x16_bf16 v[16:31], v[164:167], v[120:123], v[16:31]
	s_add_i32 m0, s21, 0xc000
	v_cndmask_b32_e64 v109, v109, v241, s[30:31]
	v_cndmask_b32_e64 v110, v110, v241, s[34:35]
	v_cndmask_b32_e64 v111, v111, v241, s[28:29]
	v_max3_f32 v246, v80, v81, v82
	v_max3_f32 v247, v83, v84, v85
	v_max3_f32 v246, v246, v86, v87
	v_max3_f32 v247, v247, v88, v89
	v_max3_f32 v246, v246, v90, v91
	v_max3_f32 v247, v247, v92, v93
	v_max3_f32 v246, v246, v94, v95
	ds_read_b64_tr_b16 v[120:121], v243 offset:54272
	ds_read_b64_tr_b16 v[122:123], v243 offset:54784
	global_load_lds_dwordx4 v224, s[4:5]
	s_add_u32 s4, s4, 0x20000
	s_addc_u32 s5, s5, 0
	s_waitcnt lgkmcnt(8)
	v_mfma_f32_32x32x16_bf16 v[0:15], v[168:171], v[124:127], v[0:15]
	v_max3_f32 v247, v247, v96, v97
	v_max3_f32 v246, v246, v98, v99
	v_max3_f32 v247, v247, v100, v101
	v_max3_f32 v246, v246, v102, v103
	v_max3_f32 v247, v247, v104, v105
	v_max3_f32 v246, v246, v106, v107
	v_max3_f32 v247, v247, v108, v109
	v_max3_f32 v246, v246, v110, v111
	v_max_f32_e32 v248, v246, v247
	ds_read_b64_tr_b16 v[124:125], v243 offset:51200
	ds_read_b64_tr_b16 v[126:127], v243 offset:51712
	v_mfma_f32_32x32x16_bf16 v[16:31], v[168:171], v[128:131], v[16:31]
	ds_read_b64_tr_b16 v[128:129], v243 offset:55296
	ds_read_b64_tr_b16 v[130:131], v243 offset:55808
	v_mfma_f32_32x32x16_bf16 v[0:15], v[172:175], v[132:135], v[0:15]
	ds_read_b64_tr_b16 v[132:133], v243 offset:52224
	ds_read_b64_tr_b16 v[134:135], v243 offset:52736
	v_mfma_f32_32x32x16_bf16 v[16:31], v[172:175], v[136:139], v[16:31]
	ds_read_b64_tr_b16 v[136:137], v243 offset:56320
	ds_read_b64_tr_b16 v[138:139], v243 offset:56832
	s_waitcnt lgkmcnt(8)
	v_mfma_f32_32x32x16_bf16 v[32:47], v[160:163], v[214:217], v[32:47]
	ds_read_b128 v[176:179], v244 offset:0
	ds_read_b128 v[180:183], v244 offset:512
	v_cmp_lt_f32_e32 vcc, s87, v248
	s_cbranch_vccnz .Lat_rare_T2o

.Lat_T2_u:
	v_add_u32_e32 v243, s16, v204
	ds_read_b64_tr_b16 v[214:215], v243 offset:24576
	ds_read_b64_tr_b16 v[216:217], v243 offset:25088
	v_mfma_f32_32x32x16_bf16 v[80:95], v[176:179], v[144:147], v[64:79]
	v_add_f32_e32 v245, v112, v113
	v_add_f32_e32 v246, v114, v115
	v_add_f32_e32 v245, v116, v245
	v_add_f32_e32 v246, v117, v246
	v_cvt_pk_bf16_f32 v160, v112, v113
	v_cvt_pk_bf16_f32 v161, v114, v115
	ds_read_b64_tr_b16 v[112:113], v243 offset:28672
	ds_read_b64_tr_b16 v[114:115], v243 offset:29184
	v_mfma_f32_32x32x16_bf16 v[96:111], v[180:183], v[144:147], v[64:79]
	v_add_f32_e32 v245, v118, v245
	v_add_f32_e32 v246, v119, v246
	v_add_f32_e32 v245, v120, v245
	v_add_f32_e32 v246, v121, v246
	v_cvt_pk_bf16_f32 v162, v116, v117
	v_cvt_pk_bf16_f32 v163, v118, v119
	ds_read_b64_tr_b16 v[116:117], v243 offset:25600
	ds_read_b64_tr_b16 v[118:119], v243 offset:26112
	v_mfma_f32_32x32x16_bf16 v[80:95], v[184:187], v[148:151], v[80:95]
	v_add_f32_e32 v245, v122, v245
	v_add_f32_e32 v246, v123, v246
	v_add_f32_e32 v245, v124, v245
	v_add_f32_e32 v246, v125, v246
	v_cvt_pk_bf16_f32 v164, v120, v121
	v_cvt_pk_bf16_f32 v165, v122, v123
	ds_read_b64_tr_b16 v[120:121], v243 offset:29696
	ds_read_b64_tr_b16 v[122:123], v243 offset:30208
	v_mfma_f32_32x32x16_bf16 v[96:111], v[188:191], v[148:151], v[96:111]
	v_add_f32_e32 v245, v126, v245
	v_add_f32_e32 v246, v127, v246
	v_add_f32_e32 v245, v128, v245
	v_add_f32_e32 v246, v129, v246
	v_cvt_pk_bf16_f32 v166, v124, v125
	v_cvt_pk_bf16_f32 v167, v126, v127
	ds_read_b64_tr_b16 v[124:125], v243 offset:26624
	ds_read_b64_tr_b16 v[126:127], v243 offset:27136
	v_mfma_f32_32x32x16_bf16 v[80:95], v[192:195], v[152:155], v[80:95]
	v_add_f32_e32 v245, v130, v245
	v_add_f32_e32 v246, v131, v246
	v_add_f32_e32 v245, v132, v245
	v_add_f32_e32 v246, v133, v246
	v_cvt_pk_bf16_f32 v168, v128, v129
	v_cvt_pk_bf16_f32 v169, v130, v131
	ds_read_b64_tr_b16 v[128:129], v243 offset:30720
	ds_read_b64_tr_b16 v[130:131], v243 offset:31232
	v_mfma_f32_32x32x16_bf16 v[96:111], v[196:199], v[152:155], v[96:111]
	v_add_f32_e32 v245, v134, v245
	v_add_f32_e32 v246, v135, v246
	v_add_f32_e32 v245, v136, v245
	v_add_f32_e32 v246, v137, v246
	v_cvt_pk_bf16_f32 v170, v132, v133
	v_cvt_pk_bf16_f32 v171, v134, v135
	ds_read_b64_tr_b16 v[132:133], v243 offset:27648
	ds_read_b64_tr_b16 v[134:135], v243 offset:28160
	v_mfma_f32_32x32x16_bf16 v[80:95], v[200:203], v[156:159], v[80:95]
	v_add_f32_e32 v245, v138, v245
	v_add_f32_e32 v246, v139, v246
	v_add_f32_e32 v245, v140, v245
	v_add_f32_e32 v246, v141, v246
	v_cvt_pk_bf16_f32 v172, v136, v137
	v_cvt_pk_bf16_f32 v173, v138, v139
	ds_read_b64_tr_b16 v[136:137], v243 offset:31744
	ds_read_b64_tr_b16 v[138:139], v243 offset:32256
	v_mfma_f32_32x32x16_bf16 v[96:111], v[206:209], v[156:159], v[96:111]
	v_add_f32_e32 v245, v142, v245
	v_add_f32_e32 v246, v143, v246
	v_add_f32_e32 v245, v245, v246
	v_cvt_pk_bf16_f32 v174, v140, v141
	v_cvt_pk_bf16_f32 v175, v142, v143
	v_add_f32_e32 v211, v211, v245
	v_add_u32_e32 v244, s18, v219
	s_waitcnt lgkmcnt(8)
	v_mfma_f32_32x32x16_bf16 v[0:15], v[160:163], v[214:217], v[0:15]
	v_max3_f32 v246, v80, v81, v82
	v_max3_f32 v247, v83, v84, v85
	ds_read_b64_tr_b16 v[214:215], v243 offset:49152
	ds_read_b64_tr_b16 v[216:217], v243 offset:49664
	v_mfma_f32_32x32x16_bf16 v[16:31], v[160:163], v[112:115], v[16:31]
	v_max3_f32 v246, v246, v86, v87
	v_max3_f32 v247, v247, v88, v89
	v_max3_f32 v246, v246, v90, v91
	v_max3_f32 v247, v247, v92, v93
	ds_read_b64_tr_b16 v[112:113], v243 offset:53248
	ds_read_b64_tr_b16 v[114:115], v243 offset:53760
	v_mfma_f32_32x32x16_bf16 v[0:15], v[164:167], v[116:119], v[0:15]
	s_add_i32 s21, s18, s54
	s_add_i32 m0, s21, 0x6000
	v_max3_f32 v246, v246, v94, v95
	v_max3_f32 v247, v247, v96, v97
	v_max3_f32 v246, v246, v98, v99
	v_max3_f32 v247, v247, v100, v101
	ds_read_b64_tr_b16 v[116:117], v243 offset:50176
	ds_read_b64_tr_b16 v[118:119], v243 offset:50688
	global_load_lds_dwordx4 v223, s[4:5]
	v_mfma_f32_32x32x16_bf16 v[16:31], v[164:167], v[120:123], v[16:31]
	s_add_i32 m0, s21, 0xc000
	v_max3_f32 v246, v246, v102, v103
	v_max3_f32 v247, v247, v104, v105
	v_max3_f32 v246, v246, v106, v107
	v_max3_f32 v247, v247, v108, v109
	ds_read_b64_tr_b16 v[120:121], v243 offset:54272
	ds_read_b64_tr_b16 v[122:123], v243 offset:54784
	global_load_lds_dwordx4 v224, s[4:5]
	s_add_u32 s4, s4, 0x20000
	s_addc_u32 s5, s5, 0
	s_waitcnt lgkmcnt(8)
	v_mfma_f32_32x32x16_bf16 v[0:15], v[168:171], v[124:127], v[0:15]
	v_max3_f32 v246, v246, v110, v111
	v_max_f32_e32 v248, v246, v247
	ds_read_b64_tr_b16 v[124:125], v243 offset:51200
	ds_read_b64_tr_b16 v[126:127], v243 offset:51712
	v_cmp_lt_f32_e32 vcc, s87, v248
	s_cbranch_vccnz .Lat_rare_T2u
.Lat_cont_T2u:
	v_mfma_f32_32x32x16_bf16 v[16:31], v[168:171], v[128:131], v[16:31]
	v_exp_f32_e32 v80, v80
	v_exp_f32_e32 v81, v81
	v_exp_f32_e32 v82, v82
	ds_read_b64_tr_b16 v[128:129], v243 offset:55296
	ds_read_b64_tr_b16 v[130:131], v243 offset:55808
	v_mfma_f32_32x32x16_bf16 v[0:15], v[172:175], v[132:135], v[0:15]
	v_exp_f32_e32 v83, v83
	v_exp_f32_e32 v84, v84
	v_exp_f32_e32 v85, v85
	ds_read_b64_tr_b16 v[132:133], v243 offset:52224
	ds_read_b64_tr_b16 v[134:135], v243 offset:52736
	v_mfma_f32_32x32x16_bf16 v[16:31], v[172:175], v[136:139], v[16:31]
	v_exp_f32_e32 v86, v86
	v_exp_f32_e32 v87, v87
	v_exp_f32_e32 v88, v88
	ds_read_b64_tr_b16 v[136:137], v243 offset:56320
	ds_read_b64_tr_b16 v[138:139], v243 offset:56832
	s_waitcnt lgkmcnt(8)
	v_mfma_f32_32x32x16_bf16 v[32:47], v[160:163], v[214:217], v[32:47]
	v_exp_f32_e32 v89, v89
	v_exp_f32_e32 v90, v90
	v_exp_f32_e32 v91, v91
	ds_read_b128 v[176:179], v244 offset:0
	ds_read_b128 v[180:183], v244 offset:512
	v_mfma_f32_32x32x16_bf16 v[48:63], v[160:163], v[112:115], v[48:63]
	v_exp_f32_e32 v92, v92
	v_exp_f32_e32 v93, v93
	v_exp_f32_e32 v94, v94
	ds_read_b128 v[184:187], v244 offset:2048
	ds_read_b128 v[188:191], v244 offset:2560
	v_mfma_f32_32x32x16_bf16 v[32:47], v[164:167], v[116:119], v[32:47]
	v_exp_f32_e32 v95, v95
	v_exp_f32_e32 v96, v96
	v_exp_f32_e32 v97, v97
	ds_read_b128 v[192:195], v244 offset:4096
	ds_read_b128 v[196:199], v244 offset:4608
	v_mfma_f32_32x32x16_bf16 v[48:63], v[164:167], v[120:123], v[48:63]
	v_exp_f32_e32 v98, v98
	v_exp_f32_e32 v99, v99
	v_exp_f32_e32 v100, v100
	ds_read_b128 v[200:203], v244 offset:6144
	ds_read_b128 v[206:209], v244 offset:6656
	s_waitcnt lgkmcnt(8)
	v_mfma_f32_32x32x16_bf16 v[32:47], v[168:171], v[124:127], v[32:47]
	v_exp_f32_e32 v101, v101
	v_exp_f32_e32 v102, v102
	v_exp_f32_e32 v103, v103
	v_mfma_f32_32x32x16_bf16 v[48:63], v[168:171], v[128:131], v[48:63]
	v_exp_f32_e32 v104, v104
	v_exp_f32_e32 v105, v105
	v_exp_f32_e32 v106, v106
	v_mfma_f32_32x32x16_bf16 v[32:47], v[172:175], v[132:135], v[32:47]
	v_exp_f32_e32 v107, v107
	v_exp_f32_e32 v108, v108
	v_exp_f32_e32 v109, v109
	v_mfma_f32_32x32x16_bf16 v[48:63], v[172:175], v[136:139], v[48:63]
	v_exp_f32_e32 v110, v110
	v_exp_f32_e32 v111, v111
	s_waitcnt vmcnt(0) lgkmcnt(0)
	s_barrier
	s_cbranch_vccnz .Lat_resc_T2u

; __device__ __forceinline__ void cmask(f32x16&p0,f32x16&p1,int jb,int qrel,int hi){
;   const float NEG=-INFINITY; int kb=64*jb+4*hi;
;   #pragma unroll
;   for(int r=0;r<16;++r){int kv=kb+(r&3)+8*(r>>2); if(kv>qrel)p0[r]=NEG; if(kv+32>qrel)p1[r]=NEG;}
; }
.Lat_T2_end:
.Lat_step_T1:
	s_cmp_lt_u32 s55, 3
	s_cbranch_scc1 .Lat_T1_light
	s_cmp_eq_u32 s55, 3
	s_cbranch_scc0 .Lat_T1_u
	s_bitcmp1_b32 s46, 5
	s_cbranch_scc1 .Lat_T1_o
	v_add_u32_e32 v243, s16, v204
	ds_read_b64_tr_b16 v[214:215], v243 offset:24576
	ds_read_b64_tr_b16 v[216:217], v243 offset:25088
	v_mfma_f32_32x32x16_bf16 v[112:127], v[176:179], v[144:147], v[64:79]
	v_add_f32_e32 v245, v80, v81
	v_add_f32_e32 v246, v82, v83
	v_add_f32_e32 v245, v84, v245
	v_add_f32_e32 v246, v85, v246
	v_cvt_pk_bf16_f32 v160, v80, v81
	v_cvt_pk_bf16_f32 v161, v82, v83
	ds_read_b64_tr_b16 v[80:81], v243 offset:28672
	ds_read_b64_tr_b16 v[82:83], v243 offset:29184
	v_mfma_f32_32x32x16_bf16 v[128:143], v[180:183], v[144:147], v[64:79]
	v_add_f32_e32 v245, v86, v245
	v_add_f32_e32 v246, v87, v246
	v_add_f32_e32 v245, v88, v245
	v_add_f32_e32 v246, v89, v246
	v_cvt_pk_bf16_f32 v162, v84, v85
	v_cvt_pk_bf16_f32 v163, v86, v87
	ds_read_b64_tr_b16 v[84:85], v243 offset:25600
	ds_read_b64_tr_b16 v[86:87], v243 offset:26112
	v_mfma_f32_32x32x16_bf16 v[112:127], v[184:187], v[148:151], v[112:127]
	v_add_f32_e32 v245, v90, v245
	v_add_f32_e32 v246, v91, v246
	v_add_f32_e32 v245, v92, v245
	v_add_f32_e32 v246, v93, v246
	v_cvt_pk_bf16_f32 v164, v88, v89
	v_cvt_pk_bf16_f32 v165, v90, v91
	ds_read_b64_tr_b16 v[88:89], v243 offset:29696
	ds_read_b64_tr_b16 v[90:91], v243 offset:30208
	v_mfma_f32_32x32x16_bf16 v[128:143], v[188:191], v[148:151], v[128:143]
	v_add_f32_e32 v245, v94, v245
	v_add_f32_e32 v246, v95, v246
	v_add_f32_e32 v245, v96, v245
	v_add_f32_e32 v246, v97, v246
	v_cvt_pk_bf16_f32 v166, v92, v93
	v_cvt_pk_bf16_f32 v167, v94, v95
	ds_read_b64_tr_b16 v[92:93], v243 offset:26624
	ds_read_b64_tr_b16 v[94:95], v243 offset:27136
	v_mfma_f32_32x32x16_bf16 v[112:127], v[192:195], v[152:155], v[112:127]
	v_add_f32_e32 v245, v98, v245
	v_add_f32_e32 v246, v99, v246
	v_add_f32_e32 v245, v100, v245
	v_add_f32_e32 v246, v101, v246
	v_cvt_pk_bf16_f32 v168, v96, v97
	v_cvt_pk_bf16_f32 v169, v98, v99
	ds_read_b64_tr_b16 v[96:97], v243 offset:30720
	ds_read_b64_tr_b16 v[98:99], v243 offset:31232
	v_mfma_f32_32x32x16_bf16 v[128:143], v[196:199], v[152:155], v[128:143]
	v_add_f32_e32 v245, v102, v245
	v_add_f32_e32 v246, v103, v246
	v_add_f32_e32 v245, v104, v245
	v_add_f32_e32 v246, v105, v246
	v_cvt_pk_bf16_f32 v170, v100, v101
	v_cvt_pk_bf16_f32 v171, v102, v103
	ds_read_b64_tr_b16 v[100:101], v243 offset:27648
	ds_read_b64_tr_b16 v[102:103], v243 offset:28160
	v_mfma_f32_32x32x16_bf16 v[112:127], v[200:203], v[156:159], v[112:127]
	v_add_f32_e32 v245, v106, v245
	v_add_f32_e32 v246, v107, v246
	v_add_f32_e32 v245, v108, v245
	v_add_f32_e32 v246, v109, v246
	v_cvt_pk_bf16_f32 v172, v104, v105
	v_cvt_pk_bf16_f32 v173, v106, v107
	ds_read_b64_tr_b16 v[104:105], v243 offset:31744
	ds_read_b64_tr_b16 v[106:107], v243 offset:32256
	v_mfma_f32_32x32x16_bf16 v[128:143], v[206:209], v[156:159], v[128:143]
	v_add_f32_e32 v245, v110, v245
	v_add_f32_e32 v246, v111, v246
	v_add_f32_e32 v245, v245, v246
	v_cvt_pk_bf16_f32 v174, v108, v109
	v_cvt_pk_bf16_f32 v175, v110, v111
	v_add_f32_e32 v211, v211, v245
	s_waitcnt lgkmcnt(8)
	v_mfma_f32_32x32x16_bf16 v[0:15], v[160:163], v[214:217], v[0:15]
	v_add_u32_e32 v242, 0xffffff40, v225
	v_cmp_gt_i32_e64 s[28:29], 0, v242
	v_cmp_gt_i32_e64 s[30:31], 1, v242
	v_cmp_gt_i32_e64 s[34:35], 2, v242
	v_cndmask_b32_e64 v112, v112, v241, s[28:29]
	v_cmp_gt_i32_e64 s[28:29], 3, v242
	v_cndmask_b32_e64 v113, v113, v241, s[30:31]
	v_cmp_gt_i32_e64 s[30:31], 8, v242
	v_cndmask_b32_e64 v114, v114, v241, s[34:35]
	v_cmp_gt_i32_e64 s[34:35], 9, v242
	ds_read_b64_tr_b16 v[214:215], v243 offset:49152
	ds_read_b64_tr_b16 v[216:217], v243 offset:49664
	v_mfma_f32_32x32x16_bf16 v[16:31], v[160:163], v[80:83], v[16:31]
	v_cndmask_b32_e64 v115, v115, v241, s[28:29]
	v_cmp_gt_i32_e64 s[28:29], 10, v242
	v_cndmask_b32_e64 v116, v116, v241, s[30:31]
	v_cmp_gt_i32_e64 s[30:31], 11, v242
	v_cndmask_b32_e64 v117, v117, v241, s[34:35]
	v_cmp_gt_i32_e64 s[34:35], 16, v242
	v_cndmask_b32_e64 v118, v118, v241, s[28:29]
	v_cmp_gt_i32_e64 s[28:29], 17, v242
	v_cndmask_b32_e64 v119, v119, v241, s[30:31]
	v_cmp_gt_i32_e64 s[30:31], 18, v242
	ds_read_b64_tr_b16 v[80:81], v243 offset:53248
	ds_read_b64_tr_b16 v[82:83], v243 offset:53760
	v_mfma_f32_32x32x16_bf16 v[0:15], v[164:167], v[84:87], v[0:15]
	v_cndmask_b32_e64 v120, v120, v241, s[34:35]
	v_cmp_gt_i32_e64 s[34:35], 19, v242
	v_cndmask_b32_e64 v121, v121, v241, s[28:29]
	v_cmp_gt_i32_e64 s[28:29], 24, v242
	v_cndmask_b32_e64 v122, v122, v241, s[30:31]
	v_cmp_gt_i32_e64 s[30:31], 25, v242
	v_cndmask_b32_e64 v123, v123, v241, s[34:35]
	v_cmp_gt_i32_e64 s[34:35], 26, v242
	v_cndmask_b32_e64 v124, v124, v241, s[28:29]
	v_cmp_gt_i32_e64 s[28:29], 27, v242
	ds_read_b64_tr_b16 v[84:85], v243 offset:50176
	ds_read_b64_tr_b16 v[86:87], v243 offset:50688
	v_mfma_f32_32x32x16_bf16 v[16:31], v[164:167], v[88:91], v[16:31]
	v_cndmask_b32_e64 v125, v125, v241, s[30:31]
	v_cndmask_b32_e64 v126, v126, v241, s[34:35]
	v_cndmask_b32_e64 v127, v127, v241, s[28:29]
	v_mov_b32_e32 v128, v241
	v_mov_b32_e32 v129, v241
	v_mov_b32_e32 v130, v241
	v_mov_b32_e32 v131, v241
	v_mov_b32_e32 v132, v241
	v_mov_b32_e32 v133, v241
	v_mov_b32_e32 v134, v241
	ds_read_b64_tr_b16 v[88:89], v243 offset:54272
	ds_read_b64_tr_b16 v[90:91], v243 offset:54784
	s_waitcnt lgkmcnt(8)
	v_mfma_f32_32x32x16_bf16 v[0:15], v[168:171], v[92:95], v[0:15]
	v_mov_b32_e32 v135, v241
	v_mov_b32_e32 v136, v241
	v_mov_b32_e32 v137, v241
	v_mov_b32_e32 v138, v241
	v_mov_b32_e32 v139, v241
	v_mov_b32_e32 v140, v241
	v_mov_b32_e32 v141, v241
	v_mov_b32_e32 v142, v241
	v_mov_b32_e32 v143, v241
	v_max3_f32 v246, v112, v113, v114
	ds_read_b64_tr_b16 v[92:93], v243 offset:51200
	ds_read_b64_tr_b16 v[94:95], v243 offset:51712
	v_mfma_f32_32x32x16_bf16 v[16:31], v[168:171], v[96:99], v[16:31]
	v_max3_f32 v247, v115, v116, v117
	v_max3_f32 v246, v246, v118, v119
	v_max3_f32 v247, v247, v120, v121
	v_max3_f32 v246, v246, v122, v123
	v_max3_f32 v247, v247, v124, v125
	v_max3_f32 v246, v246, v126, v127
	v_max3_f32 v247, v247, v128, v129
	v_max3_f32 v246, v246, v130, v131
	v_max3_f32 v247, v247, v132, v133
	v_max3_f32 v246, v246, v134, v135
	ds_read_b64_tr_b16 v[96:97], v243 offset:55296
	ds_read_b64_tr_b16 v[98:99], v243 offset:55808
	v_mfma_f32_32x32x16_bf16 v[0:15], v[172:175], v[100:103], v[0:15]
	v_max3_f32 v247, v247, v136, v137
	v_max3_f32 v246, v246, v138, v139
	v_max3_f32 v247, v247, v140, v141
	v_max3_f32 v246, v246, v142, v143
	v_max_f32_e32 v248, v246, v247
	ds_read_b64_tr_b16 v[100:101], v243 offset:52224
	ds_read_b64_tr_b16 v[102:103], v243 offset:52736
	v_mfma_f32_32x32x16_bf16 v[16:31], v[172:175], v[104:107], v[16:31]
	ds_read_b64_tr_b16 v[104:105], v243 offset:56320
	ds_read_b64_tr_b16 v[106:107], v243 offset:56832
	s_waitcnt lgkmcnt(8)
	v_mfma_f32_32x32x16_bf16 v[32:47], v[160:163], v[214:217], v[32:47]
	v_cmp_lt_f32_e32 vcc, s87, v248
	s_cbranch_vccnz .Lat_rare_T1e

; __device__ __forceinline__ void cmask(f32x16&p0,f32x16&p1,int jb,int qrel,int hi){
;   const float NEG=-INFINITY; int kb=64*jb+4*hi;
;   #pragma unroll
;   for(int r=0;r<16;++r){int kv=kb+(r&3)+8*(r>>2); if(kv>qrel)p0[r]=NEG; if(kv+32>qrel)p1[r]=NEG;}
; }
.Lat_T1_o:
	v_add_u32_e32 v243, s16, v204
	ds_read_b64_tr_b16 v[214:215], v243 offset:24576
	ds_read_b64_tr_b16 v[216:217], v243 offset:25088
	v_mfma_f32_32x32x16_bf16 v[112:127], v[176:179], v[144:147], v[64:79]
	v_add_f32_e32 v245, v80, v81
	v_add_f32_e32 v246, v82, v83
	v_add_f32_e32 v245, v84, v245
	v_add_f32_e32 v246, v85, v246
	v_cvt_pk_bf16_f32 v160, v80, v81
	v_cvt_pk_bf16_f32 v161, v82, v83
	ds_read_b64_tr_b16 v[80:81], v243 offset:28672
	ds_read_b64_tr_b16 v[82:83], v243 offset:29184
	v_mfma_f32_32x32x16_bf16 v[128:143], v[180:183], v[144:147], v[64:79]
	v_add_f32_e32 v245, v86, v245
	v_add_f32_e32 v246, v87, v246
	v_add_f32_e32 v245, v88, v245
	v_add_f32_e32 v246, v89, v246
	v_cvt_pk_bf16_f32 v162, v84, v85
	v_cvt_pk_bf16_f32 v163, v86, v87
	ds_read_b64_tr_b16 v[84:85], v243 offset:25600
	ds_read_b64_tr_b16 v[86:87], v243 offset:26112
	v_mfma_f32_32x32x16_bf16 v[112:127], v[184:187], v[148:151], v[112:127]
	v_add_f32_e32 v245, v90, v245
	v_add_f32_e32 v246, v91, v246
	v_add_f32_e32 v245, v92, v245
	v_add_f32_e32 v246, v93, v246
	v_cvt_pk_bf16_f32 v164, v88, v89
	v_cvt_pk_bf16_f32 v165, v90, v91
	ds_read_b64_tr_b16 v[88:89], v243 offset:29696
	ds_read_b64_tr_b16 v[90:91], v243 offset:30208
	v_mfma_f32_32x32x16_bf16 v[128:143], v[188:191], v[148:151], v[128:143]
	v_add_f32_e32 v245, v94, v245
	v_add_f32_e32 v246, v95, v246
	v_add_f32_e32 v245, v96, v245
	v_add_f32_e32 v246, v97, v246
	v_cvt_pk_bf16_f32 v166, v92, v93
	v_cvt_pk_bf16_f32 v167, v94, v95
	ds_read_b64_tr_b16 v[92:93], v243 offset:26624
	ds_read_b64_tr_b16 v[94:95], v243 offset:27136
	v_mfma_f32_32x32x16_bf16 v[112:127], v[192:195], v[152:155], v[112:127]
	v_add_f32_e32 v245, v98, v245
	v_add_f32_e32 v246, v99, v246
	v_add_f32_e32 v245, v100, v245
	v_add_f32_e32 v246, v101, v246
	v_cvt_pk_bf16_f32 v168, v96, v97
	v_cvt_pk_bf16_f32 v169, v98, v99
	ds_read_b64_tr_b16 v[96:97], v243 offset:30720
	ds_read_b64_tr_b16 v[98:99], v243 offset:31232
	v_mfma_f32_32x32x16_bf16 v[128:143], v[196:199], v[152:155], v[128:143]
	v_add_f32_e32 v245, v102, v245
	v_add_f32_e32 v246, v103, v246
	v_add_f32_e32 v245, v104, v245
	v_add_f32_e32 v246, v105, v246
	v_cvt_pk_bf16_f32 v170, v100, v101
	v_cvt_pk_bf16_f32 v171, v102, v103
	ds_read_b64_tr_b16 v[100:101], v243 offset:27648
	ds_read_b64_tr_b16 v[102:103], v243 offset:28160
	v_mfma_f32_32x32x16_bf16 v[112:127], v[200:203], v[156:159], v[112:127]
	v_add_f32_e32 v245, v106, v245
	v_add_f32_e32 v246, v107, v246
	v_add_f32_e32 v245, v108, v245
	v_add_f32_e32 v246, v109, v246
	v_cvt_pk_bf16_f32 v172, v104, v105
	v_cvt_pk_bf16_f32 v173, v106, v107
	ds_read_b64_tr_b16 v[104:105], v243 offset:31744
	ds_read_b64_tr_b16 v[106:107], v243 offset:32256
	v_mfma_f32_32x32x16_bf16 v[128:143], v[206:209], v[156:159], v[128:143]
	v_add_f32_e32 v245, v110, v245
	v_add_f32_e32 v246, v111, v246
	v_add_f32_e32 v245, v245, v246
	v_cvt_pk_bf16_f32 v174, v108, v109
	v_cvt_pk_bf16_f32 v175, v110, v111
	v_add_f32_e32 v211, v211, v245
	s_waitcnt lgkmcnt(8)
	v_mfma_f32_32x32x16_bf16 v[0:15], v[160:163], v[214:217], v[0:15]
	v_add_u32_e32 v242, 0xffffff40, v225
	v_cmp_gt_i32_e64 s[28:29], 32, v242
	v_cmp_gt_i32_e64 s[30:31], 33, v242
	v_cmp_gt_i32_e64 s[34:35], 34, v242
	v_cndmask_b32_e64 v128, v128, v241, s[28:29]
	v_cmp_gt_i32_e64 s[28:29], 35, v242
	v_cndmask_b32_e64 v129, v129, v241, s[30:31]
	v_cmp_gt_i32_e64 s[30:31], 40, v242
	v_cndmask_b32_e64 v130, v130, v241, s[34:35]
	v_cmp_gt_i32_e64 s[34:35], 41, v242
	ds_read_b64_tr_b16 v[214:215], v243 offset:49152
	ds_read_b64_tr_b16 v[216:217], v243 offset:49664
	v_mfma_f32_32x32x16_bf16 v[16:31], v[160:163], v[80:83], v[16:31]
	v_cndmask_b32_e64 v131, v131, v241, s[28:29]
	v_cmp_gt_i32_e64 s[28:29], 42, v242
	v_cndmask_b32_e64 v132, v132, v241, s[30:31]
	v_cmp_gt_i32_e64 s[30:31], 43, v242
	v_cndmask_b32_e64 v133, v133, v241, s[34:35]
	v_cmp_gt_i32_e64 s[34:35], 48, v242
	v_cndmask_b32_e64 v134, v134, v241, s[28:29]
	v_cmp_gt_i32_e64 s[28:29], 49, v242
	v_cndmask_b32_e64 v135, v135, v241, s[30:31]
	v_cmp_gt_i32_e64 s[30:31], 50, v242
	ds_read_b64_tr_b16 v[80:81], v243 offset:53248
	ds_read_b64_tr_b16 v[82:83], v243 offset:53760
	v_mfma_f32_32x32x16_bf16 v[0:15], v[164:167], v[84:87], v[0:15]
	v_cndmask_b32_e64 v136, v136, v241, s[34:35]
	v_cmp_gt_i32_e64 s[34:35], 51, v242
	v_cndmask_b32_e64 v137, v137, v241, s[28:29]
	v_cmp_gt_i32_e64 s[28:29], 56, v242
	v_cndmask_b32_e64 v138, v138, v241, s[30:31]
	v_cmp_gt_i32_e64 s[30:31], 57, v242
	v_cndmask_b32_e64 v139, v139, v241, s[34:35]
	v_cmp_gt_i32_e64 s[34:35], 58, v242
	v_cndmask_b32_e64 v140, v140, v241, s[28:29]
	v_cmp_gt_i32_e64 s[28:29], 59, v242
	ds_read_b64_tr_b16 v[84:85], v243 offset:50176
	ds_read_b64_tr_b16 v[86:87], v243 offset:50688
	v_mfma_f32_32x32x16_bf16 v[16:31], v[164:167], v[88:91], v[16:31]
	v_cndmask_b32_e64 v141, v141, v241, s[30:31]
	v_cndmask_b32_e64 v142, v142, v241, s[34:35]
	v_cndmask_b32_e64 v143, v143, v241, s[28:29]
	v_max3_f32 v246, v112, v113, v114
	v_max3_f32 v247, v115, v116, v117
	v_max3_f32 v246, v246, v118, v119
	v_max3_f32 v247, v247, v120, v121
	v_max3_f32 v246, v246, v122, v123
	v_max3_f32 v247, v247, v124, v125
	v_max3_f32 v246, v246, v126, v127
	ds_read_b64_tr_b16 v[88:89], v243 offset:54272
	ds_read_b64_tr_b16 v[90:91], v243 offset:54784
	s_waitcnt lgkmcnt(8)
	v_mfma_f32_32x32x16_bf16 v[0:15], v[168:171], v[92:95], v[0:15]
	v_max3_f32 v247, v247, v128, v129
	v_max3_f32 v246, v246, v130, v131
	v_max3_f32 v247, v247, v132, v133
	v_max3_f32 v246, v246, v134, v135
	v_max3_f32 v247, v247, v136, v137
	v_max3_f32 v246, v246, v138, v139
	v_max3_f32 v247, v247, v140, v141
	v_max3_f32 v246, v246, v142, v143
	v_max_f32_e32 v248, v246, v247
	ds_read_b64_tr_b16 v[92:93], v243 offset:51200
	ds_read_b64_tr_b16 v[94:95], v243 offset:51712
	v_mfma_f32_32x32x16_bf16 v[16:31], v[168:171], v[96:99], v[16:31]
	ds_read_b64_tr_b16 v[96:97], v243 offset:55296
	ds_read_b64_tr_b16 v[98:99], v243 offset:55808
	v_mfma_f32_32x32x16_bf16 v[0:15], v[172:175], v[100:103], v[0:15]
	ds_read_b64_tr_b16 v[100:101], v243 offset:52224
	ds_read_b64_tr_b16 v[102:103], v243 offset:52736
	v_mfma_f32_32x32x16_bf16 v[16:31], v[172:175], v[104:107], v[16:31]
	ds_read_b64_tr_b16 v[104:105], v243 offset:56320
	ds_read_b64_tr_b16 v[106:107], v243 offset:56832
	s_waitcnt lgkmcnt(8)
	v_mfma_f32_32x32x16_bf16 v[32:47], v[160:163], v[214:217], v[32:47]
	v_cmp_lt_f32_e32 vcc, s87, v248
	s_cbranch_vccnz .Lat_rare_T1o

.Lat_T1_u:
	v_add_u32_e32 v243, s16, v204
	ds_read_b64_tr_b16 v[214:215], v243 offset:24576
	ds_read_b64_tr_b16 v[216:217], v243 offset:25088
	v_mfma_f32_32x32x16_bf16 v[112:127], v[176:179], v[144:147], v[64:79]
	v_add_f32_e32 v245, v80, v81
	v_add_f32_e32 v246, v82, v83
	v_add_f32_e32 v245, v84, v245
	v_add_f32_e32 v246, v85, v246
	v_cvt_pk_bf16_f32 v160, v80, v81
	v_cvt_pk_bf16_f32 v161, v82, v83
	ds_read_b64_tr_b16 v[80:81], v243 offset:28672
	ds_read_b64_tr_b16 v[82:83], v243 offset:29184
	v_mfma_f32_32x32x16_bf16 v[128:143], v[180:183], v[144:147], v[64:79]
	v_add_f32_e32 v245, v86, v245
	v_add_f32_e32 v246, v87, v246
	v_add_f32_e32 v245, v88, v245
	v_add_f32_e32 v246, v89, v246
	v_cvt_pk_bf16_f32 v162, v84, v85
	v_cvt_pk_bf16_f32 v163, v86, v87
	ds_read_b64_tr_b16 v[84:85], v243 offset:25600
	ds_read_b64_tr_b16 v[86:87], v243 offset:26112
	v_mfma_f32_32x32x16_bf16 v[112:127], v[184:187], v[148:151], v[112:127]
	v_add_f32_e32 v245, v90, v245
	v_add_f32_e32 v246, v91, v246
	v_add_f32_e32 v245, v92, v245
	v_add_f32_e32 v246, v93, v246
	v_cvt_pk_bf16_f32 v164, v88, v89
	v_cvt_pk_bf16_f32 v165, v90, v91
	ds_read_b64_tr_b16 v[88:89], v243 offset:29696
	ds_read_b64_tr_b16 v[90:91], v243 offset:30208
	v_mfma_f32_32x32x16_bf16 v[128:143], v[188:191], v[148:151], v[128:143]
	v_add_f32_e32 v245, v94, v245
	v_add_f32_e32 v246, v95, v246
	v_add_f32_e32 v245, v96, v245
	v_add_f32_e32 v246, v97, v246
	v_cvt_pk_bf16_f32 v166, v92, v93
	v_cvt_pk_bf16_f32 v167, v94, v95
	ds_read_b64_tr_b16 v[92:93], v243 offset:26624
	ds_read_b64_tr_b16 v[94:95], v243 offset:27136
	v_mfma_f32_32x32x16_bf16 v[112:127], v[192:195], v[152:155], v[112:127]
	v_add_f32_e32 v245, v98, v245
	v_add_f32_e32 v246, v99, v246
	v_add_f32_e32 v245, v100, v245
	v_add_f32_e32 v246, v101, v246
	v_cvt_pk_bf16_f32 v168, v96, v97
	v_cvt_pk_bf16_f32 v169, v98, v99
	ds_read_b64_tr_b16 v[96:97], v243 offset:30720
	ds_read_b64_tr_b16 v[98:99], v243 offset:31232
	v_mfma_f32_32x32x16_bf16 v[128:143], v[196:199], v[152:155], v[128:143]
	v_add_f32_e32 v245, v102, v245
	v_add_f32_e32 v246, v103, v246
	v_add_f32_e32 v245, v104, v245
	v_add_f32_e32 v246, v105, v246
	v_cvt_pk_bf16_f32 v170, v100, v101
	v_cvt_pk_bf16_f32 v171, v102, v103
	ds_read_b64_tr_b16 v[100:101], v243 offset:27648
	ds_read_b64_tr_b16 v[102:103], v243 offset:28160
	v_mfma_f32_32x32x16_bf16 v[112:127], v[200:203], v[156:159], v[112:127]
	v_add_f32_e32 v245, v106, v245
	v_add_f32_e32 v246, v107, v246
	v_add_f32_e32 v245, v108, v245
	v_add_f32_e32 v246, v109, v246
	v_cvt_pk_bf16_f32 v172, v104, v105
	v_cvt_pk_bf16_f32 v173, v106, v107
	ds_read_b64_tr_b16 v[104:105], v243 offset:31744
	ds_read_b64_tr_b16 v[106:107], v243 offset:32256
	v_mfma_f32_32x32x16_bf16 v[128:143], v[206:209], v[156:159], v[128:143]
	v_add_f32_e32 v245, v110, v245
	v_add_f32_e32 v246, v111, v246
	v_add_f32_e32 v245, v245, v246
	v_cvt_pk_bf16_f32 v174, v108, v109
	v_cvt_pk_bf16_f32 v175, v110, v111
	v_add_f32_e32 v211, v211, v245
	s_waitcnt lgkmcnt(8)
	v_mfma_f32_32x32x16_bf16 v[0:15], v[160:163], v[214:217], v[0:15]
	v_max3_f32 v246, v112, v113, v114
	v_max3_f32 v247, v115, v116, v117
	ds_read_b64_tr_b16 v[214:215], v243 offset:49152
	ds_read_b64_tr_b16 v[216:217], v243 offset:49664
	v_mfma_f32_32x32x16_bf16 v[16:31], v[160:163], v[80:83], v[16:31]
	v_max3_f32 v246, v246, v118, v119
	v_max3_f32 v247, v247, v120, v121
	v_max3_f32 v246, v246, v122, v123
	v_max3_f32 v247, v247, v124, v125
	ds_read_b64_tr_b16 v[80:81], v243 offset:53248
	ds_read_b64_tr_b16 v[82:83], v243 offset:53760
	v_mfma_f32_32x32x16_bf16 v[0:15], v[164:167], v[84:87], v[0:15]
	v_max3_f32 v246, v246, v126, v127
	v_max3_f32 v247, v247, v128, v129
	v_max3_f32 v246, v246, v130, v131
	v_max3_f32 v247, v247, v132, v133
	ds_read_b64_tr_b16 v[84:85], v243 offset:50176
	ds_read_b64_tr_b16 v[86:87], v243 offset:50688
	v_mfma_f32_32x32x16_bf16 v[16:31], v[164:167], v[88:91], v[16:31]
	v_max3_f32 v246, v246, v134, v135
	v_max3_f32 v247, v247, v136, v137
	v_max3_f32 v246, v246, v138, v139
	v_max3_f32 v247, v247, v140, v141
	ds_read_b64_tr_b16 v[88:89], v243 offset:54272
	ds_read_b64_tr_b16 v[90:91], v243 offset:54784
	s_waitcnt lgkmcnt(8)
	v_mfma_f32_32x32x16_bf16 v[0:15], v[168:171], v[92:95], v[0:15]
	v_max3_f32 v246, v246, v142, v143
	v_max_f32_e32 v248, v246, v247
	ds_read_b64_tr_b16 v[92:93], v243 offset:51200
	ds_read_b64_tr_b16 v[94:95], v243 offset:51712
	v_cmp_lt_f32_e32 vcc, s87, v248
	s_cbranch_vccnz .Lat_rare_T1u
.Lat_cont_T1u:
	v_mfma_f32_32x32x16_bf16 v[16:31], v[168:171], v[96:99], v[16:31]
	v_exp_f32_e32 v112, v112
	v_exp_f32_e32 v113, v113
	v_exp_f32_e32 v114, v114
	ds_read_b64_tr_b16 v[96:97], v243 offset:55296
	ds_read_b64_tr_b16 v[98:99], v243 offset:55808
	v_mfma_f32_32x32x16_bf16 v[0:15], v[172:175], v[100:103], v[0:15]
	v_exp_f32_e32 v115, v115
	v_exp_f32_e32 v116, v116
	v_exp_f32_e32 v117, v117
	ds_read_b64_tr_b16 v[100:101], v243 offset:52224
	ds_read_b64_tr_b16 v[102:103], v243 offset:52736
	v_mfma_f32_32x32x16_bf16 v[16:31], v[172:175], v[104:107], v[16:31]
	v_exp_f32_e32 v118, v118
	v_exp_f32_e32 v119, v119
	v_exp_f32_e32 v120, v120
	ds_read_b64_tr_b16 v[104:105], v243 offset:56320
	ds_read_b64_tr_b16 v[106:107], v243 offset:56832
	s_waitcnt lgkmcnt(8)
	v_mfma_f32_32x32x16_bf16 v[32:47], v[160:163], v[214:217], v[32:47]
	v_exp_f32_e32 v121, v121
	v_exp_f32_e32 v122, v122
	v_exp_f32_e32 v123, v123
	v_mfma_f32_32x32x16_bf16 v[48:63], v[160:163], v[80:83], v[48:63]
	v_exp_f32_e32 v124, v124
	v_exp_f32_e32 v125, v125
	v_exp_f32_e32 v126, v126
	v_mfma_f32_32x32x16_bf16 v[32:47], v[164:167], v[84:87], v[32:47]
	v_exp_f32_e32 v127, v127
	v_exp_f32_e32 v128, v128
	v_exp_f32_e32 v129, v129
	v_mfma_f32_32x32x16_bf16 v[48:63], v[164:167], v[88:91], v[48:63]
	v_exp_f32_e32 v130, v130
	v_exp_f32_e32 v131, v131
	v_exp_f32_e32 v132, v132
	s_waitcnt lgkmcnt(0)
	v_mfma_f32_32x32x16_bf16 v[32:47], v[168:171], v[92:95], v[32:47]
	v_exp_f32_e32 v133, v133
	v_exp_f32_e32 v134, v134
	v_exp_f32_e32 v135, v135
	v_mfma_f32_32x32x16_bf16 v[48:63], v[168:171], v[96:99], v[48:63]
	v_exp_f32_e32 v136, v136
	v_exp_f32_e32 v137, v137
	v_exp_f32_e32 v138, v138
	v_mfma_f32_32x32x16_bf16 v[32:47], v[172:175], v[100:103], v[32:47]
	v_exp_f32_e32 v139, v139
	v_exp_f32_e32 v140, v140
	v_exp_f32_e32 v141, v141
	v_mfma_f32_32x32x16_bf16 v[48:63], v[172:175], v[104:107], v[48:63]
	v_exp_f32_e32 v142, v142
	v_exp_f32_e32 v143, v143
	s_cbranch_vccnz .Lat_resc_T1u
